# P0 slimmed: w_in transpose hand-written; WA/WB/WO/VTC transposes + KC convert moved to P1 tail (96 idle WGs)
# speedup vs baseline: 1.0106x; 1.0075x over previous
; #define LAS __attribute__((address_space(3)))
; template <int MODE>
; __device__ __forceinline__ void transpose_item(const float* W, int N, bf16_t* WT, int ldt, int coff, LAS float* scr, int item, int lane, const float* g) {
;     const int nblk = N / 32, kb = item / nblk, nb = item % nblk, k0 = 64 * kb, n0 = 32 * nb;
; #pragma unroll 8
;     for (int i = 0; i < 32; ++i) { const int kk = 2 * i + (lane >> 5); float v = W[(size_t)(k0 + kk) * N + n0 + (lane & 31)]; if (MODE >= 1) v *= g[k0 + kk]; scr[kk * 33 + (lane & 31)] = v; }
; __global__ void __launch_bounds__(512, 2) mk_fwd(Args a) {
;     ...
;     if (IN(0)) {
;         constexpr int I_IN = 32 * 320, I_A = 16 * 64, I_O = 32 * 64, I_V = 16 * 32;
;         constexpr int NIT = I_IN + 2 * I_A + I_O + 16 * I_V;
;         for (int it = gw; it < NIT; it += NGW) {
;             int r = it;
;             if (r < I_IN) { transpose_item<2>(a.in[I_WIN], NIN, WIN, DM, 0, scr, r, lane, a.in[I_N1]); continue; } r -= I_IN;
.LBB0_17:
	s_load_dwordx16 s[36:51], s[0:1], 0x0
	s_load_dwordx16 s[52:67], s[0:1], 0x40
	s_lshr_b32 s1, s14, 6
	s_lshl_b32 s0, s2, 3
	s_add_i32 s96, s1, s0
	s_lshl_b32 s80, s3, 3
	s_add_u32 s82, s68, 0x100000
	s_addc_u32 s83, s69, 0
	s_add_u32 s4, s68, 0x2900000
	s_addc_u32 s5, s69, 0
	s_add_u32 s94, s68, 0x3100000
	s_addc_u32 s95, s69, 0
	s_add_u32 s33, s68, 0x18b00000
	s_addc_u32 s14, s69, 0
	s_lshl_b32 s0, s1, 14
	s_add_i32 s6, s0, 0
	v_writelane_b32 v250, s4, 5
	s_cmp_lt_i32 s70, 1
	v_lshlrev_b32_e32 v221, 3, v179
	v_writelane_b32 v250, s5, 6
	s_cselect_b64 s[4:5], -1, 0
	s_cmp_gt_i32 s71, 0
	v_writelane_b32 v250, s1, 7
	s_cselect_b64 s[0:1], -1, 0
	s_and_b64 s[0:1], s[4:5], s[0:1]
	v_bfe_u32 v181, v179, 3, 3
	v_and_b32_e32 v202, 56, v221
	v_and_b32_e32 v201, 31, v179
	v_mul_u32_u24_e32 v0, 0x84, v202
	v_lshlrev_b32_e32 v1, 2, v181
	s_cmpk_lt_i32 s96, 0x4400
	v_lshl_add_u32 v180, v201, 2, s6
	v_add3_u32 v187, s6, v0, v1
	s_cselect_b64 s[6:7], -1, 0
	v_writelane_b32 v250, s6, 8
	v_and_b32_e32 v220, 63, v179
	s_ashr_i32 s81, s80, 31
	v_writelane_b32 v250, s7, 9
	v_bfe_u32 v178, v179, 5, 1
	v_mov_b32_e32 v177, 0
	v_or_b32_e32 v198, 8, v181
	v_or_b32_e32 v199, 16, v181
	v_or_b32_e32 v200, 24, v181
	s_ashr_i32 s97, s96, 31
	v_lshlrev_b32_e32 v176, 3, v220
	s_andn2_b64 vcc, exec, s[0:1]
	v_writelane_b32 v250, s80, 10
	s_nop 1
	v_writelane_b32 v250, s81, 11
	s_cbranch_vccnz .LBB0_71
	s_waitcnt lgkmcnt(0)
	s_and_b32 s0, s96, 7
	s_lshl_b32 s0, s0, 14
	s_cmp_lt_u32 s96, 0x2800
	s_cbranch_scc0 .Ltr_done_p0in
	v_lshrrev_b32_e32 v0, 3, v220
	v_and_b32_e32 v1, 7, v220
	v_mul_u32_u24_e32 v2, 0xa000, v0
	v_lshl_add_u32 v36, v1, 4, v2
	v_add_u32_e32 v37, 0x50000, v36
	v_add_u32_e32 v72, 0xa0000, v36
	v_add_u32_e32 v73, 0xf0000, v36
	v_add_u32_e32 v74, 0x140000, v36
	v_add_u32_e32 v75, 0x190000, v36
	v_add_u32_e32 v76, 0x1e0000, v36
	v_add_u32_e32 v182, 0x230000, v36
	v_mul_u32_u24_e32 v2, 0x84, v0
	v_lshl_add_u32 v2, v1, 4, v2
	v_add_u32_e32 v196, s0, v2
	v_mul_u32_u24_e32 v2, 0x420, v1
	v_lshl_add_u32 v2, v0, 2, v2
	v_add_u32_e32 v197, s0, v2
	v_mul_u32_u24_e32 v2, 0x1000, v0
	v_lshl_add_u32 v183, v1, 4, v2
	v_add_u32_e32 v184, 0x8000, v183
	v_add_u32_e32 v185, 0x10000, v183
	v_add_u32_e32 v186, 0x18000, v183
	v_lshlrev_b32_e32 v203, 5, v1
	s_mov_b32 s7, s96
	s_mov_b32 s1, s96
	s_lshr_b32 s9, s1, 6
	s_mul_hi_u32 s9, s9, 0xcccccccd
	s_lshr_b32 s9, s9, 2
	s_mul_i32 s15, s9, 0x140
	s_sub_u32 s15, s1, s15
	s_mul_i32 s32, s9, 0x280000
	s_lshl_b32 s15, s15, 7
	s_add_u32 s32, s32, s15
	s_add_u32 s10, s52, s32
	s_addc_u32 s11, s53, 0
	global_load_dwordx4 v[4:7], v36, s[10:11]
	global_load_dwordx4 v[8:11], v37, s[10:11]
	global_load_dwordx4 v[12:15], v72, s[10:11]
	global_load_dwordx4 v[16:19], v73, s[10:11]
	global_load_dwordx4 v[20:23], v74, s[10:11]
	global_load_dwordx4 v[24:27], v75, s[10:11]
	global_load_dwordx4 v[28:31], v76, s[10:11]
	global_load_dwordx4 v[32:35], v182, s[10:11]
	s_lshl_b32 s32, s9, 8
	s_add_u32 s72, s50, s32
	s_addc_u32 s73, s51, 0
	global_load_dwordx4 v[188:191], v203, s[72:73]
	global_load_dwordx4 v[192:195], v203, s[72:73] offset:16
	s_add_u32 s1, s1, 0x800
	s_cmp_lt_u32 s1, 0x2800
	s_cbranch_scc0 .Ltr_p1_p0in
	s_lshr_b32 s9, s1, 6
	s_mul_hi_u32 s9, s9, 0xcccccccd
	s_lshr_b32 s9, s9, 2
	s_mul_i32 s15, s9, 0x140
	s_sub_u32 s15, s1, s15
	s_mul_i32 s32, s9, 0x280000
	s_lshl_b32 s15, s15, 7
	s_add_u32 s32, s32, s15
	s_add_u32 s10, s52, s32
	s_addc_u32 s11, s53, 0
	global_load_dwordx4 v[40:43], v36, s[10:11]
	global_load_dwordx4 v[44:47], v37, s[10:11]
	global_load_dwordx4 v[48:51], v72, s[10:11]
	global_load_dwordx4 v[52:55], v73, s[10:11]
	global_load_dwordx4 v[56:59], v74, s[10:11]
	global_load_dwordx4 v[60:63], v75, s[10:11]
	global_load_dwordx4 v[64:67], v76, s[10:11]
	global_load_dwordx4 v[68:71], v182, s[10:11]
	s_lshl_b32 s32, s9, 8
	s_add_u32 s72, s50, s32
	s_addc_u32 s73, s51, 0
	global_load_dwordx4 v[224:227], v203, s[72:73]
	global_load_dwordx4 v[228:231], v203, s[72:73] offset:16
.Ltr_p1_p0in:
	s_add_u32 s1, s1, 0x800
.Ltr_st0_p0in:
	s_cmp_lt_u32 s1, 0x2800
	s_cbranch_scc0 .Ltr_nl0_p0in
	s_lshr_b32 s9, s1, 6
	s_mul_hi_u32 s9, s9, 0xcccccccd
	s_lshr_b32 s9, s9, 2
	s_mul_i32 s15, s9, 0x140
	s_sub_u32 s15, s1, s15
	s_mul_i32 s32, s9, 0x280000
	s_lshl_b32 s15, s15, 7
	s_add_u32 s32, s32, s15
	s_add_u32 s10, s52, s32
	s_addc_u32 s11, s53, 0
	global_load_dwordx4 v[96:99], v36, s[10:11]
	global_load_dwordx4 v[100:103], v37, s[10:11]
	global_load_dwordx4 v[104:107], v72, s[10:11]
	global_load_dwordx4 v[108:111], v73, s[10:11]
	global_load_dwordx4 v[112:115], v74, s[10:11]
	global_load_dwordx4 v[116:119], v75, s[10:11]
	global_load_dwordx4 v[120:123], v76, s[10:11]
	global_load_dwordx4 v[124:127], v182, s[10:11]
	s_lshl_b32 s32, s9, 8
	s_add_u32 s72, s50, s32
	s_addc_u32 s73, s51, 0
	global_load_dwordx4 v[232:235], v203, s[72:73]
	global_load_dwordx4 v[236:239], v203, s[72:73] offset:16
	s_waitcnt vmcnt(20)
	s_branch .Ltr_pr0_p0in
.Ltr_nl0_p0in:
	s_sub_u32 s9, s1, 0x800
	s_cmp_lt_u32 s9, 0x2800
	s_cbranch_scc0 .Ltr_w00_p0in
	s_waitcnt vmcnt(10)
	s_branch .Ltr_pr0_p0in

; #define LAS __attribute__((address_space(3)))
; __device__ __forceinline__ unsigned cvtpk(float lo, float hi) { f32x2_t v = {lo, hi}; bf16x2_t b = __builtin_convertvector(v, bf16x2_t); return __builtin_bit_cast(unsigned, b); }
; template <int MODE>
; __device__ __forceinline__ void transpose_item(const float* W, int N, bf16_t* WT, int ldt, int coff, LAS float* scr, int item, int lane, const float* g) {
;     const int nblk = N / 32, kb = item / nblk, nb = item % nblk, k0 = 64 * kb, n0 = 32 * nb;
; #pragma unroll 8
;     for (int i = 0; i < 32; ++i) { const int kk = 2 * i + (lane >> 5); float v = W[(size_t)(k0 + kk) * N + n0 + (lane & 31)]; if (MODE >= 1) v *= g[k0 + kk]; scr[kk * 33 + (lane & 31)] = v; }
;     asm volatile("s_waitcnt lgkmcnt(0)" ::: "memory");
;     const int c = lane & 7;
; #pragma unroll
;     for (int j = 0; j < 4; ++j) {
;         const int n = (lane >> 3) + 8 * j; const LAS float* s = scr + (8 * c) * 33 + n;
;         u32x4 o; o.x = cvtpk(s[0 * 33], s[1 * 33]); o.y = cvtpk(s[2 * 33], s[3 * 33]); o.z = cvtpk(s[4 * 33], s[5 * 33]); o.w = cvtpk(s[6 * 33], s[7 * 33]);
;         int dr = n0 + n;
;         if (MODE == 1) { dr = (dr < DFF) ? 256 * (dr >> 7) + (dr & 127) : 256 * ((dr - DFF) >> 7) + 128 + ((dr - DFF) & 127); }
;         if (MODE == 2) {
;             if (dr >= 6144) { const int t = dr - 6144, ch = t & 2047; dr = 6144 + 256 * (ch >> 7) + ((t >> 11) << 7) + (ch & 127); }
;             else if (dr >= 4096) { const int t = dr - 4096, ch = t & 1023; dr = 4096 + 256 * (ch >> 7) + ((t >> 10) << 7) + (ch & 127); }
;         }
;         *(u32x4*)(WT + (size_t)dr * ldt + coff + k0 + 8 * c) = o;
.Ltr_pr0_p0in:
	s_add_u32 s1, s1, 0x800
	s_lshr_b32 s9, s7, 6
	s_mul_hi_u32 s9, s9, 0xcccccccd
	s_lshr_b32 s9, s9, 2
	s_mul_i32 s15, s9, 0x140
	s_sub_u32 s15, s7, s15
	s_lshl_b32 s15, s15, 5
	s_movk_i32 s32, 0x1000
	s_cmp_ge_u32 s15, 0x1800
	s_cselect_b32 s32, 0x1800, s32
	s_cselect_b32 s74, 11, 10
	s_cmp_lt_u32 s15, 0x1000
	s_cbranch_scc1 .Ltr_m2lin_p0in_0
	s_sub_u32 s15, s15, s32
	s_lshr_b32 s34, s15, s74
	s_lshl_b32 s34, s34, 7
	s_add_u32 s32, s32, s34
	s_bfm_b32 s34, s74, 0
	s_and_b32 s15, s15, s34
	s_and_b32 s34, s15, 0x7f
	s_add_u32 s32, s32, s34
	s_and_b32 s15, s15, 0xffffff80
	s_lshl_b32 s15, s15, 1
	s_add_u32 s15, s32, s15
.Ltr_m2lin_p0in_0:
	s_mul_i32 s32, s15, 0x1000
	s_lshl_b32 s9, s9, 7
	s_add_u32 s32, s32, s9
	s_add_u32 s34, s82, s32
	s_addc_u32 s35, s83, 0
	ds_write_b32 v196, v4 offset:0
	ds_write_b32 v196, v5 offset:4
	ds_write_b32 v196, v6 offset:8
	ds_write_b32 v196, v7 offset:12
	ds_write_b32 v196, v8 offset:1056
	ds_write_b32 v196, v9 offset:1060
	ds_write_b32 v196, v10 offset:1064
	ds_write_b32 v196, v11 offset:1068
	ds_write_b32 v196, v12 offset:2112
	ds_write_b32 v196, v13 offset:2116
	ds_write_b32 v196, v14 offset:2120
	ds_write_b32 v196, v15 offset:2124
	ds_write_b32 v196, v16 offset:3168
	ds_write_b32 v196, v17 offset:3172
	ds_write_b32 v196, v18 offset:3176
	ds_write_b32 v196, v19 offset:3180
	ds_write_b32 v196, v20 offset:4224
	ds_write_b32 v196, v21 offset:4228
	ds_write_b32 v196, v22 offset:4232
	ds_write_b32 v196, v23 offset:4236
	ds_write_b32 v196, v24 offset:5280
	ds_write_b32 v196, v25 offset:5284
	ds_write_b32 v196, v26 offset:5288
	ds_write_b32 v196, v27 offset:5292
	ds_write_b32 v196, v28 offset:6336
	ds_write_b32 v196, v29 offset:6340
	ds_write_b32 v196, v30 offset:6344
	ds_write_b32 v196, v31 offset:6348
	ds_write_b32 v196, v32 offset:7392
	ds_write_b32 v196, v33 offset:7396
	ds_write_b32 v196, v34 offset:7400
	ds_write_b32 v196, v35 offset:7404
	s_waitcnt lgkmcnt(0)
	ds_read2_b32 v[128:129], v197 offset0:0 offset1:8
	ds_read2_b32 v[132:133], v197 offset0:33 offset1:41
	ds_read2_b32 v[136:137], v197 offset0:66 offset1:74
	ds_read2_b32 v[140:141], v197 offset0:99 offset1:107
	ds_read2_b32 v[144:145], v197 offset0:132 offset1:140
	ds_read2_b32 v[148:149], v197 offset0:165 offset1:173
	ds_read2_b32 v[152:153], v197 offset0:198 offset1:206
	ds_read2_b32 v[156:157], v197 offset0:231 offset1:239
	ds_read2_b32 v[130:131], v197 offset0:16 offset1:24
	ds_read2_b32 v[134:135], v197 offset0:49 offset1:57
	ds_read2_b32 v[138:139], v197 offset0:82 offset1:90
	ds_read2_b32 v[142:143], v197 offset0:115 offset1:123
	ds_read2_b32 v[146:147], v197 offset0:148 offset1:156
	ds_read2_b32 v[150:151], v197 offset0:181 offset1:189
	ds_read2_b32 v[154:155], v197 offset0:214 offset1:222
	ds_read2_b32 v[158:159], v197 offset0:247 offset1:255
	s_waitcnt lgkmcnt(0)
	v_mul_f32_e32 v128, v188, v128
	v_mul_f32_e32 v129, v188, v129
	v_mul_f32_e32 v130, v188, v130
	v_mul_f32_e32 v131, v188, v131
	v_mul_f32_e32 v132, v189, v132
	v_mul_f32_e32 v133, v189, v133
	v_mul_f32_e32 v134, v189, v134
	v_mul_f32_e32 v135, v189, v135
	v_mul_f32_e32 v136, v190, v136
	v_mul_f32_e32 v137, v190, v137
	v_mul_f32_e32 v138, v190, v138
	v_mul_f32_e32 v139, v190, v139
	v_mul_f32_e32 v140, v191, v140
	v_mul_f32_e32 v141, v191, v141
	v_mul_f32_e32 v142, v191, v142
	v_mul_f32_e32 v143, v191, v143
	v_mul_f32_e32 v144, v192, v144
	v_mul_f32_e32 v145, v192, v145
	v_mul_f32_e32 v146, v192, v146
	v_mul_f32_e32 v147, v192, v147
	v_mul_f32_e32 v148, v193, v148
	v_mul_f32_e32 v149, v193, v149
	v_mul_f32_e32 v150, v193, v150
	v_mul_f32_e32 v151, v193, v151
	v_mul_f32_e32 v152, v194, v152
	v_mul_f32_e32 v153, v194, v153
	v_mul_f32_e32 v154, v194, v154
	v_mul_f32_e32 v155, v194, v155
	v_mul_f32_e32 v156, v195, v156
	v_mul_f32_e32 v157, v195, v157
	v_mul_f32_e32 v158, v195, v158
	v_mul_f32_e32 v159, v195, v159
	v_cvt_pk_bf16_f32 v204, v128, v132
	v_cvt_pk_bf16_f32 v205, v136, v140
	v_cvt_pk_bf16_f32 v206, v144, v148
	v_cvt_pk_bf16_f32 v207, v152, v156
	global_store_dwordx4 v183, v[204:207], s[34:35]
	v_cvt_pk_bf16_f32 v208, v129, v133
	v_cvt_pk_bf16_f32 v209, v137, v141
	v_cvt_pk_bf16_f32 v210, v145, v149
	v_cvt_pk_bf16_f32 v211, v153, v157
	global_store_dwordx4 v184, v[208:211], s[34:35]
	v_cvt_pk_bf16_f32 v212, v130, v134
	v_cvt_pk_bf16_f32 v213, v138, v142
	v_cvt_pk_bf16_f32 v214, v146, v150
	v_cvt_pk_bf16_f32 v215, v154, v158
	global_store_dwordx4 v185, v[212:215], s[34:35]
	v_cvt_pk_bf16_f32 v216, v131, v135
	v_cvt_pk_bf16_f32 v217, v139, v143
	v_cvt_pk_bf16_f32 v218, v147, v151
	v_cvt_pk_bf16_f32 v219, v155, v159
	global_store_dwordx4 v186, v[216:219], s[34:35]
	s_add_u32 s7, s7, 0x800
	s_cmp_lt_u32 s7, 0x2800
	s_cbranch_scc0 .Ltr_done_p0in
.Ltr_st1_p0in:
	s_cmp_lt_u32 s1, 0x2800
	s_cbranch_scc0 .Ltr_nl1_p0in
	s_lshr_b32 s9, s1, 6
	s_mul_hi_u32 s9, s9, 0xcccccccd
	s_lshr_b32 s9, s9, 2
	s_mul_i32 s15, s9, 0x140
	s_sub_u32 s15, s1, s15
	s_mul_i32 s32, s9, 0x280000
	s_lshl_b32 s15, s15, 7
	s_add_u32 s32, s32, s15
	s_add_u32 s10, s52, s32
	s_addc_u32 s11, s53, 0
	global_load_dwordx4 v[4:7], v36, s[10:11]
	global_load_dwordx4 v[8:11], v37, s[10:11]
	global_load_dwordx4 v[12:15], v72, s[10:11]
	global_load_dwordx4 v[16:19], v73, s[10:11]
	global_load_dwordx4 v[20:23], v74, s[10:11]
	global_load_dwordx4 v[24:27], v75, s[10:11]
	global_load_dwordx4 v[28:31], v76, s[10:11]
	global_load_dwordx4 v[32:35], v182, s[10:11]
	s_lshl_b32 s32, s9, 8
	s_add_u32 s72, s50, s32
	s_addc_u32 s73, s51, 0
	global_load_dwordx4 v[188:191], v203, s[72:73]
	global_load_dwordx4 v[192:195], v203, s[72:73] offset:16
	s_waitcnt vmcnt(20)
	s_branch .Ltr_pr1_p0in

; #define LAS __attribute__((address_space(3)))
; __device__ __forceinline__ unsigned cvtpk(float lo, float hi) { f32x2_t v = {lo, hi}; bf16x2_t b = __builtin_convertvector(v, bf16x2_t); return __builtin_bit_cast(unsigned, b); }
; template <int MODE>
; __device__ __forceinline__ void transpose_item(const float* W, int N, bf16_t* WT, int ldt, int coff, LAS float* scr, int item, int lane, const float* g) {
;     const int nblk = N / 32, kb = item / nblk, nb = item % nblk, k0 = 64 * kb, n0 = 32 * nb;
; #pragma unroll 8
;     for (int i = 0; i < 32; ++i) { const int kk = 2 * i + (lane >> 5); float v = W[(size_t)(k0 + kk) * N + n0 + (lane & 31)]; if (MODE >= 1) v *= g[k0 + kk]; scr[kk * 33 + (lane & 31)] = v; }
;     asm volatile("s_waitcnt lgkmcnt(0)" ::: "memory");
;     const int c = lane & 7;
; #pragma unroll
;     for (int j = 0; j < 4; ++j) {
;         const int n = (lane >> 3) + 8 * j; const LAS float* s = scr + (8 * c) * 33 + n;
;         u32x4 o; o.x = cvtpk(s[0 * 33], s[1 * 33]); o.y = cvtpk(s[2 * 33], s[3 * 33]); o.z = cvtpk(s[4 * 33], s[5 * 33]); o.w = cvtpk(s[6 * 33], s[7 * 33]);
;         int dr = n0 + n;
;         if (MODE == 1) { dr = (dr < DFF) ? 256 * (dr >> 7) + (dr & 127) : 256 * ((dr - DFF) >> 7) + 128 + ((dr - DFF) & 127); }
;         if (MODE == 2) {
;             if (dr >= 6144) { const int t = dr - 6144, ch = t & 2047; dr = 6144 + 256 * (ch >> 7) + ((t >> 11) << 7) + (ch & 127); }
;             else if (dr >= 4096) { const int t = dr - 4096, ch = t & 1023; dr = 4096 + 256 * (ch >> 7) + ((t >> 10) << 7) + (ch & 127); }
;         }
;         *(u32x4*)(WT + (size_t)dr * ldt + coff + k0 + 8 * c) = o;
;     }
;     asm volatile("s_waitcnt lgkmcnt(0)" ::: "memory");
; }
.Ltr_m2lin_p0in_1:
	s_mul_i32 s32, s15, 0x1000
	s_lshl_b32 s9, s9, 7
	s_add_u32 s32, s32, s9
	s_add_u32 s34, s82, s32
	s_addc_u32 s35, s83, 0
	ds_write_b32 v196, v40 offset:0
	ds_write_b32 v196, v41 offset:4
	ds_write_b32 v196, v42 offset:8
	ds_write_b32 v196, v43 offset:12
	ds_write_b32 v196, v44 offset:1056
	ds_write_b32 v196, v45 offset:1060
	ds_write_b32 v196, v46 offset:1064
	ds_write_b32 v196, v47 offset:1068
	ds_write_b32 v196, v48 offset:2112
	ds_write_b32 v196, v49 offset:2116
	ds_write_b32 v196, v50 offset:2120
	ds_write_b32 v196, v51 offset:2124
	ds_write_b32 v196, v52 offset:3168
	ds_write_b32 v196, v53 offset:3172
	ds_write_b32 v196, v54 offset:3176
	ds_write_b32 v196, v55 offset:3180
	ds_write_b32 v196, v56 offset:4224
	ds_write_b32 v196, v57 offset:4228
	ds_write_b32 v196, v58 offset:4232
	ds_write_b32 v196, v59 offset:4236
	ds_write_b32 v196, v60 offset:5280
	ds_write_b32 v196, v61 offset:5284
	ds_write_b32 v196, v62 offset:5288
	ds_write_b32 v196, v63 offset:5292
	ds_write_b32 v196, v64 offset:6336
	ds_write_b32 v196, v65 offset:6340
	ds_write_b32 v196, v66 offset:6344
	ds_write_b32 v196, v67 offset:6348
	ds_write_b32 v196, v68 offset:7392
	ds_write_b32 v196, v69 offset:7396
	ds_write_b32 v196, v70 offset:7400
	ds_write_b32 v196, v71 offset:7404
	s_waitcnt lgkmcnt(0)
	ds_read2_b32 v[128:129], v197 offset0:0 offset1:8
	ds_read2_b32 v[132:133], v197 offset0:33 offset1:41
	ds_read2_b32 v[136:137], v197 offset0:66 offset1:74
	ds_read2_b32 v[140:141], v197 offset0:99 offset1:107
	ds_read2_b32 v[144:145], v197 offset0:132 offset1:140
	ds_read2_b32 v[148:149], v197 offset0:165 offset1:173
	ds_read2_b32 v[152:153], v197 offset0:198 offset1:206
	ds_read2_b32 v[156:157], v197 offset0:231 offset1:239
	ds_read2_b32 v[130:131], v197 offset0:16 offset1:24
	ds_read2_b32 v[134:135], v197 offset0:49 offset1:57
	ds_read2_b32 v[138:139], v197 offset0:82 offset1:90
	ds_read2_b32 v[142:143], v197 offset0:115 offset1:123
	ds_read2_b32 v[146:147], v197 offset0:148 offset1:156
	ds_read2_b32 v[150:151], v197 offset0:181 offset1:189
	ds_read2_b32 v[154:155], v197 offset0:214 offset1:222
	ds_read2_b32 v[158:159], v197 offset0:247 offset1:255
	s_waitcnt lgkmcnt(0)
	v_mul_f32_e32 v128, v224, v128
	v_mul_f32_e32 v129, v224, v129
	v_mul_f32_e32 v130, v224, v130
	v_mul_f32_e32 v131, v224, v131
	v_mul_f32_e32 v132, v225, v132
	v_mul_f32_e32 v133, v225, v133
	v_mul_f32_e32 v134, v225, v134
	v_mul_f32_e32 v135, v225, v135
	v_mul_f32_e32 v136, v226, v136
	v_mul_f32_e32 v137, v226, v137
	v_mul_f32_e32 v138, v226, v138
	v_mul_f32_e32 v139, v226, v139
	v_mul_f32_e32 v140, v227, v140
	v_mul_f32_e32 v141, v227, v141
	v_mul_f32_e32 v142, v227, v142
	v_mul_f32_e32 v143, v227, v143
	v_mul_f32_e32 v144, v228, v144
	v_mul_f32_e32 v145, v228, v145
	v_mul_f32_e32 v146, v228, v146
	v_mul_f32_e32 v147, v228, v147
	v_mul_f32_e32 v148, v229, v148
	v_mul_f32_e32 v149, v229, v149
	v_mul_f32_e32 v150, v229, v150
	v_mul_f32_e32 v151, v229, v151
	v_mul_f32_e32 v152, v230, v152
	v_mul_f32_e32 v153, v230, v153
	v_mul_f32_e32 v154, v230, v154
	v_mul_f32_e32 v155, v230, v155
	v_mul_f32_e32 v156, v231, v156
	v_mul_f32_e32 v157, v231, v157
	v_mul_f32_e32 v158, v231, v158
	v_mul_f32_e32 v159, v231, v159
	v_cvt_pk_bf16_f32 v204, v128, v132
	v_cvt_pk_bf16_f32 v205, v136, v140
	v_cvt_pk_bf16_f32 v206, v144, v148
	v_cvt_pk_bf16_f32 v207, v152, v156
	global_store_dwordx4 v183, v[204:207], s[34:35]
	v_cvt_pk_bf16_f32 v208, v129, v133
	v_cvt_pk_bf16_f32 v209, v137, v141
	v_cvt_pk_bf16_f32 v210, v145, v149
	v_cvt_pk_bf16_f32 v211, v153, v157
	global_store_dwordx4 v184, v[208:211], s[34:35]
	v_cvt_pk_bf16_f32 v212, v130, v134
	v_cvt_pk_bf16_f32 v213, v138, v142
	v_cvt_pk_bf16_f32 v214, v146, v150
	v_cvt_pk_bf16_f32 v215, v154, v158
	global_store_dwordx4 v185, v[212:215], s[34:35]
	v_cvt_pk_bf16_f32 v216, v131, v135
	v_cvt_pk_bf16_f32 v217, v139, v143
	v_cvt_pk_bf16_f32 v218, v147, v151
	v_cvt_pk_bf16_f32 v219, v155, v159
	global_store_dwordx4 v186, v[216:219], s[34:35]
	s_add_u32 s7, s7, 0x800
	s_cmp_lt_u32 s7, 0x2800
	s_cbranch_scc0 .Ltr_done_p0in
.Ltr_st2_p0in:
	s_cmp_lt_u32 s1, 0x2800
	s_cbranch_scc0 .Ltr_nl2_p0in
	s_lshr_b32 s9, s1, 6
	s_mul_hi_u32 s9, s9, 0xcccccccd
	s_lshr_b32 s9, s9, 2
	s_mul_i32 s15, s9, 0x140
	s_sub_u32 s15, s1, s15
	s_mul_i32 s32, s9, 0x280000
	s_lshl_b32 s15, s15, 7
	s_add_u32 s32, s32, s15
	s_add_u32 s10, s52, s32
	s_addc_u32 s11, s53, 0
	global_load_dwordx4 v[40:43], v36, s[10:11]
	global_load_dwordx4 v[44:47], v37, s[10:11]
	global_load_dwordx4 v[48:51], v72, s[10:11]
	global_load_dwordx4 v[52:55], v73, s[10:11]
	global_load_dwordx4 v[56:59], v74, s[10:11]
	global_load_dwordx4 v[60:63], v75, s[10:11]
	global_load_dwordx4 v[64:67], v76, s[10:11]
	global_load_dwordx4 v[68:71], v182, s[10:11]
	s_lshl_b32 s32, s9, 8
	s_add_u32 s72, s50, s32
	s_addc_u32 s73, s51, 0
	global_load_dwordx4 v[224:227], v203, s[72:73]
	global_load_dwordx4 v[228:231], v203, s[72:73] offset:16
	s_waitcnt vmcnt(20)
	s_branch .Ltr_pr2_p0in

; #define LAS __attribute__((address_space(3)))
; __device__ __forceinline__ unsigned cvtpk(float lo, float hi) { f32x2_t v = {lo, hi}; bf16x2_t b = __builtin_convertvector(v, bf16x2_t); return __builtin_bit_cast(unsigned, b); }
; template <int MODE>
; __device__ __forceinline__ void transpose_item(const float* W, int N, bf16_t* WT, int ldt, int coff, LAS float* scr, int item, int lane, const float* g) {
;     const int nblk = N / 32, kb = item / nblk, nb = item % nblk, k0 = 64 * kb, n0 = 32 * nb;
; #pragma unroll 8
;     for (int i = 0; i < 32; ++i) { const int kk = 2 * i + (lane >> 5); float v = W[(size_t)(k0 + kk) * N + n0 + (lane & 31)]; if (MODE >= 1) v *= g[k0 + kk]; scr[kk * 33 + (lane & 31)] = v; }
;     asm volatile("s_waitcnt lgkmcnt(0)" ::: "memory");
;     const int c = lane & 7;
; #pragma unroll
;     for (int j = 0; j < 4; ++j) {
;         const int n = (lane >> 3) + 8 * j; const LAS float* s = scr + (8 * c) * 33 + n;
;         u32x4 o; o.x = cvtpk(s[0 * 33], s[1 * 33]); o.y = cvtpk(s[2 * 33], s[3 * 33]); o.z = cvtpk(s[4 * 33], s[5 * 33]); o.w = cvtpk(s[6 * 33], s[7 * 33]);
;         int dr = n0 + n;
;         if (MODE == 1) { dr = (dr < DFF) ? 256 * (dr >> 7) + (dr & 127) : 256 * ((dr - DFF) >> 7) + 128 + ((dr - DFF) & 127); }
;         if (MODE == 2) {
;             if (dr >= 6144) { const int t = dr - 6144, ch = t & 2047; dr = 6144 + 256 * (ch >> 7) + ((t >> 11) << 7) + (ch & 127); }
;             else if (dr >= 4096) { const int t = dr - 4096, ch = t & 1023; dr = 4096 + 256 * (ch >> 7) + ((t >> 10) << 7) + (ch & 127); }
;         }
;         *(u32x4*)(WT + (size_t)dr * ldt + coff + k0 + 8 * c) = o;
;     }
;     asm volatile("s_waitcnt lgkmcnt(0)" ::: "memory");
; }
.Ltr_m2lin_p0in_2:
	s_mul_i32 s32, s15, 0x1000
	s_lshl_b32 s9, s9, 7
	s_add_u32 s32, s32, s9
	s_add_u32 s34, s82, s32
	s_addc_u32 s35, s83, 0
	ds_write_b32 v196, v96 offset:0
	ds_write_b32 v196, v97 offset:4
	ds_write_b32 v196, v98 offset:8
	ds_write_b32 v196, v99 offset:12
	ds_write_b32 v196, v100 offset:1056
	ds_write_b32 v196, v101 offset:1060
	ds_write_b32 v196, v102 offset:1064
	ds_write_b32 v196, v103 offset:1068
	ds_write_b32 v196, v104 offset:2112
	ds_write_b32 v196, v105 offset:2116
	ds_write_b32 v196, v106 offset:2120
	ds_write_b32 v196, v107 offset:2124
	ds_write_b32 v196, v108 offset:3168
	ds_write_b32 v196, v109 offset:3172
	ds_write_b32 v196, v110 offset:3176
	ds_write_b32 v196, v111 offset:3180
	ds_write_b32 v196, v112 offset:4224
	ds_write_b32 v196, v113 offset:4228
	ds_write_b32 v196, v114 offset:4232
	ds_write_b32 v196, v115 offset:4236
	ds_write_b32 v196, v116 offset:5280
	ds_write_b32 v196, v117 offset:5284
	ds_write_b32 v196, v118 offset:5288
	ds_write_b32 v196, v119 offset:5292
	ds_write_b32 v196, v120 offset:6336
	ds_write_b32 v196, v121 offset:6340
	ds_write_b32 v196, v122 offset:6344
	ds_write_b32 v196, v123 offset:6348
	ds_write_b32 v196, v124 offset:7392
	ds_write_b32 v196, v125 offset:7396
	ds_write_b32 v196, v126 offset:7400
	ds_write_b32 v196, v127 offset:7404
	s_waitcnt lgkmcnt(0)
	ds_read2_b32 v[128:129], v197 offset0:0 offset1:8
	ds_read2_b32 v[132:133], v197 offset0:33 offset1:41
	ds_read2_b32 v[136:137], v197 offset0:66 offset1:74
	ds_read2_b32 v[140:141], v197 offset0:99 offset1:107
	ds_read2_b32 v[144:145], v197 offset0:132 offset1:140
	ds_read2_b32 v[148:149], v197 offset0:165 offset1:173
	ds_read2_b32 v[152:153], v197 offset0:198 offset1:206
	ds_read2_b32 v[156:157], v197 offset0:231 offset1:239
	ds_read2_b32 v[130:131], v197 offset0:16 offset1:24
	ds_read2_b32 v[134:135], v197 offset0:49 offset1:57
	ds_read2_b32 v[138:139], v197 offset0:82 offset1:90
	ds_read2_b32 v[142:143], v197 offset0:115 offset1:123
	ds_read2_b32 v[146:147], v197 offset0:148 offset1:156
	ds_read2_b32 v[150:151], v197 offset0:181 offset1:189
	ds_read2_b32 v[154:155], v197 offset0:214 offset1:222
	ds_read2_b32 v[158:159], v197 offset0:247 offset1:255
	s_waitcnt lgkmcnt(0)
	v_mul_f32_e32 v128, v232, v128
	v_mul_f32_e32 v129, v232, v129
	v_mul_f32_e32 v130, v232, v130
	v_mul_f32_e32 v131, v232, v131
	v_mul_f32_e32 v132, v233, v132
	v_mul_f32_e32 v133, v233, v133
	v_mul_f32_e32 v134, v233, v134
	v_mul_f32_e32 v135, v233, v135
	v_mul_f32_e32 v136, v234, v136
	v_mul_f32_e32 v137, v234, v137
	v_mul_f32_e32 v138, v234, v138
	v_mul_f32_e32 v139, v234, v139
	v_mul_f32_e32 v140, v235, v140
	v_mul_f32_e32 v141, v235, v141
	v_mul_f32_e32 v142, v235, v142
	v_mul_f32_e32 v143, v235, v143
	v_mul_f32_e32 v144, v236, v144
	v_mul_f32_e32 v145, v236, v145
	v_mul_f32_e32 v146, v236, v146
	v_mul_f32_e32 v147, v236, v147
	v_mul_f32_e32 v148, v237, v148
	v_mul_f32_e32 v149, v237, v149
	v_mul_f32_e32 v150, v237, v150
	v_mul_f32_e32 v151, v237, v151
	v_mul_f32_e32 v152, v238, v152
	v_mul_f32_e32 v153, v238, v153
	v_mul_f32_e32 v154, v238, v154
	v_mul_f32_e32 v155, v238, v155
	v_mul_f32_e32 v156, v239, v156
	v_mul_f32_e32 v157, v239, v157
	v_mul_f32_e32 v158, v239, v158
	v_mul_f32_e32 v159, v239, v159
	v_cvt_pk_bf16_f32 v204, v128, v132
	v_cvt_pk_bf16_f32 v205, v136, v140
	v_cvt_pk_bf16_f32 v206, v144, v148
	v_cvt_pk_bf16_f32 v207, v152, v156
	global_store_dwordx4 v183, v[204:207], s[34:35]
	v_cvt_pk_bf16_f32 v208, v129, v133
	v_cvt_pk_bf16_f32 v209, v137, v141
	v_cvt_pk_bf16_f32 v210, v145, v149
	v_cvt_pk_bf16_f32 v211, v153, v157
	global_store_dwordx4 v184, v[208:211], s[34:35]
	v_cvt_pk_bf16_f32 v212, v130, v134
	v_cvt_pk_bf16_f32 v213, v138, v142
	v_cvt_pk_bf16_f32 v214, v146, v150
	v_cvt_pk_bf16_f32 v215, v154, v158
	global_store_dwordx4 v185, v[212:215], s[34:35]
	v_cvt_pk_bf16_f32 v216, v131, v135
	v_cvt_pk_bf16_f32 v217, v139, v143
	v_cvt_pk_bf16_f32 v218, v147, v151
	v_cvt_pk_bf16_f32 v219, v155, v159
	global_store_dwordx4 v186, v[216:219], s[34:35]
	s_add_u32 s7, s7, 0x800
	s_cmp_lt_u32 s7, 0x2800
	s_cbranch_scc0 .Ltr_done_p0in
	s_branch .Ltr_st0_p0in

; __global__ void __launch_bounds__(512, 2) mk_fwd(Args a) {
;     ...
;         for (size_t i = (size_t)gw; i < (size_t)DBATCH * PAST * 1024 / 512; i += NGW) {
;             const float* s = a.in[I_CK] + i * 512 + lane * 8; const f32x4 v0 = *(const f32x4*)s, v1 = *(const f32x4*)(s + 4);
;             store_bf8(KC + i * 512 + lane * 8, v0, v1);
;         }
.LBB0_68:
	s_cmp_eq_u32 s3, 0x100
	s_cbranch_scc1 .LBB0_71
	s_lshl_b64 s[0:1], s[96:97], 10
	s_add_u32 s0, s68, s0
	v_lshlrev_b32_e32 v2, 4, v220
	v_mov_b32_e32 v3, 0
	s_addc_u32 s1, s69, s1
	v_lshl_add_u64 v[0:1], s[0:1], 0, v[2:3]
	s_mov_b64 s[0:1], 0x16b00000
	v_lshl_add_u64 v[0:1], v[0:1], 0, s[0:1]
	s_lshl_b64 s[0:1], s[80:81], 10
	s_lshl_b64 s[6:7], s[96:97], 11
	s_waitcnt lgkmcnt(0)
	s_add_u32 s6, s40, s6
	v_lshlrev_b32_e32 v2, 5, v220
	s_addc_u32 s7, s41, s7
	v_lshl_add_u64 v[2:3], s[6:7], 0, v[2:3]
	v_lshl_add_u64 v[2:3], v[2:3], 0, 16
	s_lshl_b64 s[6:7], s[80:81], 11
	v_mov_b64_e32 v[4:5], 0x8000
	s_mov_b64 s[8:9], s[96:97]

; #define PG8_WAIT_V(n) asm volatile("s_waitcnt vmcnt(" #n ")" ::: "memory")
; #define PG8_BAR __builtin_amdgcn_s_barrier()
; template <class Epi>
; __device__ __forceinline__ void gemm_phase(LAS unsigned char* lds, const Gemm g, const StaticOrder& S, const Epi& E) {
;     ...
;     PG8_WAIT_V(0);
;     PG8_BAR;
; __global__ void __launch_bounds__(512, 2) mk_fwd(Args a) {
;     ...
;             if (r < I_A) { transpose_item<0>(a.in[I_WA], DM, WAB, 2048, 0, scr, r, lane, nullptr); continue; } r -= I_A;
;             if (r < I_A) { transpose_item<0>(a.in[I_WB], DM, WAB, 2048, 1024, scr, r, lane, nullptr); continue; } r -= I_A;
.LBB0_415:
	s_waitcnt vmcnt(0)
	v_readlane_b32 s96, v250, 16
	v_readlane_b32 s94, v250, 12
	v_readlane_b32 s10, v250, 14
	v_readlane_b32 s97, v250, 17
	v_readlane_b32 s95, v250, 13
	v_readlane_b32 s11, v250, 15
	s_barrier
	s_cmp_eq_u32 s3, 0x100
	s_cbranch_scc0 .Ltail_done
	s_cmp_ge_u32 s2, 0xa0
	s_cbranch_scc0 .Ltail_done
	v_readlane_b32 s0, v250, 0
	v_readlane_b32 s1, v250, 1
	s_nop 3
	s_sub_u32 s0, s0, 0xd0
	s_subb_u32 s1, s1, 0
	s_load_dwordx2 s[4:5], s[0:1], 0x78
	s_load_dwordx2 s[6:7], s[0:1], 0x80
	s_load_dwordx2 s[8:9], s[0:1], 0x88
	s_load_dwordx2 s[18:19], s[0:1], 0x18
	s_load_dwordx2 s[34:35], s[0:1], 0x10
	s_add_u32 s36, s68, 0x2900000
	s_addc_u32 s37, s69, 0
	s_add_u32 s40, s68, 0x2900800
	s_addc_u32 s41, s69, 0
	s_add_u32 s72, s68, 0x3100000
	s_addc_u32 s73, s69, 0
	s_add_u32 s74, s68, 0x18b00000
	s_addc_u32 s75, s69, 0
	s_add_u32 s76, s68, 0x16b00000
	s_addc_u32 s77, s69, 0
	s_lshl_b32 s67, s2, 3
	v_readfirstlane_b32 s32, v179
	s_nop 3
	s_lshr_b32 s32, s32, 6
	s_add_u32 s67, s67, s32
	s_sub_u32 s67, s67, 0x500
	s_lshl_b32 s32, s32, 14
	s_waitcnt lgkmcnt(0)
	s_cmp_lt_u32 s67, 0x400
	s_cbranch_scc0 .Ltr_done_t1wa
	v_lshrrev_b32_e32 v0, 3, v220
	v_and_b32_e32 v1, 7, v220
	v_mul_u32_u24_e32 v2, 0x2000, v0
	v_lshl_add_u32 v36, v1, 4, v2
	v_add_u32_e32 v37, 0x10000, v36
	v_add_u32_e32 v72, 0x20000, v36
	v_add_u32_e32 v73, 0x30000, v36
	v_add_u32_e32 v74, 0x40000, v36
	v_add_u32_e32 v75, 0x50000, v36
	v_add_u32_e32 v76, 0x60000, v36
	v_add_u32_e32 v182, 0x70000, v36
	v_mul_u32_u24_e32 v2, 0x84, v0
	v_lshl_add_u32 v2, v1, 4, v2
	v_add_u32_e32 v188, s32, v2
	v_mul_u32_u24_e32 v2, 0x420, v1
	v_lshl_add_u32 v2, v0, 2, v2
	v_add_u32_e32 v189, s32, v2
	v_mul_u32_u24_e32 v2, 0x1000, v0
	v_lshl_add_u32 v183, v1, 4, v2
	v_add_u32_e32 v184, 0x8000, v183
	v_add_u32_e32 v185, 0x10000, v183
	v_add_u32_e32 v186, 0x18000, v183
	s_mov_b32 s81, s67
	s_mov_b32 s79, s67
	s_lshr_b32 s86, s79, 6
	s_and_b32 s87, s79, 0x3f
	s_mul_i32 s88, s86, 0x80000
	s_lshl_b32 s87, s87, 7
	s_add_u32 s88, s88, s87
	s_add_u32 s82, s4, s88
	s_addc_u32 s83, s5, 0
	global_load_dwordx4 v[4:7], v36, s[82:83]
	global_load_dwordx4 v[8:11], v37, s[82:83]
	global_load_dwordx4 v[12:15], v72, s[82:83]
	global_load_dwordx4 v[16:19], v73, s[82:83]
	global_load_dwordx4 v[20:23], v74, s[82:83]
	global_load_dwordx4 v[24:27], v75, s[82:83]
	global_load_dwordx4 v[28:31], v76, s[82:83]
	global_load_dwordx4 v[32:35], v182, s[82:83]
	s_add_u32 s79, s79, 0x300
	s_cmp_lt_u32 s79, 0x400
	s_cbranch_scc0 .Ltr_p1_t1wa
	s_lshr_b32 s86, s79, 6
	s_and_b32 s87, s79, 0x3f
	s_mul_i32 s88, s86, 0x80000
	s_lshl_b32 s87, s87, 7
	s_add_u32 s88, s88, s87
	s_add_u32 s82, s4, s88
	s_addc_u32 s83, s5, 0
	global_load_dwordx4 v[40:43], v36, s[82:83]
	global_load_dwordx4 v[44:47], v37, s[82:83]
	global_load_dwordx4 v[48:51], v72, s[82:83]
	global_load_dwordx4 v[52:55], v73, s[82:83]
	global_load_dwordx4 v[56:59], v74, s[82:83]
	global_load_dwordx4 v[60:63], v75, s[82:83]
	global_load_dwordx4 v[64:67], v76, s[82:83]
	global_load_dwordx4 v[68:71], v182, s[82:83]
.Ltr_p1_t1wa:
	s_add_u32 s79, s79, 0x300
.Ltr_st0_t1wa:
	s_cmp_lt_u32 s79, 0x400
	s_cbranch_scc0 .Ltr_nl0_t1wa
	s_lshr_b32 s86, s79, 6
	s_and_b32 s87, s79, 0x3f
	s_mul_i32 s88, s86, 0x80000
	s_lshl_b32 s87, s87, 7
	s_add_u32 s88, s88, s87
	s_add_u32 s82, s4, s88
	s_addc_u32 s83, s5, 0
	global_load_dwordx4 v[96:99], v36, s[82:83]
	global_load_dwordx4 v[100:103], v37, s[82:83]
	global_load_dwordx4 v[104:107], v72, s[82:83]
	global_load_dwordx4 v[108:111], v73, s[82:83]
	global_load_dwordx4 v[112:115], v74, s[82:83]
	global_load_dwordx4 v[116:119], v75, s[82:83]
	global_load_dwordx4 v[120:123], v76, s[82:83]
	global_load_dwordx4 v[124:127], v182, s[82:83]
	s_waitcnt vmcnt(16)
	s_branch .Ltr_pr0_t1wa
.Ltr_nl0_t1wa:
	s_sub_u32 s86, s79, 0x300
	s_cmp_lt_u32 s86, 0x400
	s_cbranch_scc0 .Ltr_w00_t1wa
	s_waitcnt vmcnt(8)
	s_branch .Ltr_pr0_t1wa

; #define LAS __attribute__((address_space(3)))
; __device__ __forceinline__ unsigned cvtpk(float lo, float hi) { f32x2_t v = {lo, hi}; bf16x2_t b = __builtin_convertvector(v, bf16x2_t); return __builtin_bit_cast(unsigned, b); }
; template <int MODE>
; __device__ __forceinline__ void transpose_item(const float* W, int N, bf16_t* WT, int ldt, int coff, LAS float* scr, int item, int lane, const float* g) {
;     const int nblk = N / 32, kb = item / nblk, nb = item % nblk, k0 = 64 * kb, n0 = 32 * nb;
; #pragma unroll 8
;     for (int i = 0; i < 32; ++i) { const int kk = 2 * i + (lane >> 5); float v = W[(size_t)(k0 + kk) * N + n0 + (lane & 31)]; if (MODE >= 1) v *= g[k0 + kk]; scr[kk * 33 + (lane & 31)] = v; }
;     asm volatile("s_waitcnt lgkmcnt(0)" ::: "memory");
;     const int c = lane & 7;
; #pragma unroll
;     for (int j = 0; j < 4; ++j) {
;         const int n = (lane >> 3) + 8 * j; const LAS float* s = scr + (8 * c) * 33 + n;
;         u32x4 o; o.x = cvtpk(s[0 * 33], s[1 * 33]); o.y = cvtpk(s[2 * 33], s[3 * 33]); o.z = cvtpk(s[4 * 33], s[5 * 33]); o.w = cvtpk(s[6 * 33], s[7 * 33]);
;         int dr = n0 + n;
;         if (MODE == 1) { dr = (dr < DFF) ? 256 * (dr >> 7) + (dr & 127) : 256 * ((dr - DFF) >> 7) + 128 + ((dr - DFF) & 127); }
;         if (MODE == 2) {
;             if (dr >= 6144) { const int t = dr - 6144, ch = t & 2047; dr = 6144 + 256 * (ch >> 7) + ((t >> 11) << 7) + (ch & 127); }
;             else if (dr >= 4096) { const int t = dr - 4096, ch = t & 1023; dr = 4096 + 256 * (ch >> 7) + ((t >> 10) << 7) + (ch & 127); }
;         }
;         *(u32x4*)(WT + (size_t)dr * ldt + coff + k0 + 8 * c) = o;
;     }
;     asm volatile("s_waitcnt lgkmcnt(0)" ::: "memory");
; }
.Ltr_pr0_t1wa:
	s_add_u32 s79, s79, 0x300
	s_lshr_b32 s86, s81, 6
	s_and_b32 s87, s81, 0x3f
	s_mul_i32 s88, s87, 0x20000
	s_lshl_b32 s86, s86, 7
	s_add_u32 s88, s88, s86
	s_add_u32 s84, s36, s88
	s_addc_u32 s85, s37, 0
	ds_write_b32 v188, v4 offset:0
	ds_write_b32 v188, v5 offset:4
	ds_write_b32 v188, v6 offset:8
	ds_write_b32 v188, v7 offset:12
	ds_write_b32 v188, v8 offset:1056
	ds_write_b32 v188, v9 offset:1060
	ds_write_b32 v188, v10 offset:1064
	ds_write_b32 v188, v11 offset:1068
	ds_write_b32 v188, v12 offset:2112
	ds_write_b32 v188, v13 offset:2116
	ds_write_b32 v188, v14 offset:2120
	ds_write_b32 v188, v15 offset:2124
	ds_write_b32 v188, v16 offset:3168
	ds_write_b32 v188, v17 offset:3172
	ds_write_b32 v188, v18 offset:3176
	ds_write_b32 v188, v19 offset:3180
	ds_write_b32 v188, v20 offset:4224
	ds_write_b32 v188, v21 offset:4228
	ds_write_b32 v188, v22 offset:4232
	ds_write_b32 v188, v23 offset:4236
	ds_write_b32 v188, v24 offset:5280
	ds_write_b32 v188, v25 offset:5284
	ds_write_b32 v188, v26 offset:5288
	ds_write_b32 v188, v27 offset:5292
	ds_write_b32 v188, v28 offset:6336
	ds_write_b32 v188, v29 offset:6340
	ds_write_b32 v188, v30 offset:6344
	ds_write_b32 v188, v31 offset:6348
	ds_write_b32 v188, v32 offset:7392
	ds_write_b32 v188, v33 offset:7396
	ds_write_b32 v188, v34 offset:7400
	ds_write_b32 v188, v35 offset:7404
	s_waitcnt lgkmcnt(0)
	ds_read2_b32 v[128:129], v189 offset0:0 offset1:8
	ds_read2_b32 v[132:133], v189 offset0:33 offset1:41
	ds_read2_b32 v[136:137], v189 offset0:66 offset1:74
	ds_read2_b32 v[140:141], v189 offset0:99 offset1:107
	ds_read2_b32 v[144:145], v189 offset0:132 offset1:140
	ds_read2_b32 v[148:149], v189 offset0:165 offset1:173
	ds_read2_b32 v[152:153], v189 offset0:198 offset1:206
	ds_read2_b32 v[156:157], v189 offset0:231 offset1:239
	ds_read2_b32 v[130:131], v189 offset0:16 offset1:24
	ds_read2_b32 v[134:135], v189 offset0:49 offset1:57
	ds_read2_b32 v[138:139], v189 offset0:82 offset1:90
	ds_read2_b32 v[142:143], v189 offset0:115 offset1:123
	ds_read2_b32 v[146:147], v189 offset0:148 offset1:156
	ds_read2_b32 v[150:151], v189 offset0:181 offset1:189
	ds_read2_b32 v[154:155], v189 offset0:214 offset1:222
	ds_read2_b32 v[158:159], v189 offset0:247 offset1:255
	s_waitcnt lgkmcnt(0)
	v_cvt_pk_bf16_f32 v204, v128, v132
	v_cvt_pk_bf16_f32 v205, v136, v140
	v_cvt_pk_bf16_f32 v206, v144, v148
	v_cvt_pk_bf16_f32 v207, v152, v156
	global_store_dwordx4 v183, v[204:207], s[84:85]
	v_cvt_pk_bf16_f32 v208, v129, v133
	v_cvt_pk_bf16_f32 v209, v137, v141
	v_cvt_pk_bf16_f32 v210, v145, v149
	v_cvt_pk_bf16_f32 v211, v153, v157
	global_store_dwordx4 v184, v[208:211], s[84:85]
	v_cvt_pk_bf16_f32 v212, v130, v134
	v_cvt_pk_bf16_f32 v213, v138, v142
	v_cvt_pk_bf16_f32 v214, v146, v150
	v_cvt_pk_bf16_f32 v215, v154, v158
	global_store_dwordx4 v185, v[212:215], s[84:85]
	v_cvt_pk_bf16_f32 v216, v131, v135
	v_cvt_pk_bf16_f32 v217, v139, v143
	v_cvt_pk_bf16_f32 v218, v147, v151
	v_cvt_pk_bf16_f32 v219, v155, v159
	global_store_dwordx4 v186, v[216:219], s[84:85]
	s_add_u32 s81, s81, 0x300
	s_cmp_lt_u32 s81, 0x400
	s_cbranch_scc0 .Ltr_done_t1wa
.Ltr_st1_t1wa:
	s_cmp_lt_u32 s79, 0x400
	s_cbranch_scc0 .Ltr_nl1_t1wa
	s_lshr_b32 s86, s79, 6
	s_and_b32 s87, s79, 0x3f
	s_mul_i32 s88, s86, 0x80000
	s_lshl_b32 s87, s87, 7
	s_add_u32 s88, s88, s87
	s_add_u32 s82, s4, s88
	s_addc_u32 s83, s5, 0
	global_load_dwordx4 v[4:7], v36, s[82:83]
	global_load_dwordx4 v[8:11], v37, s[82:83]
	global_load_dwordx4 v[12:15], v72, s[82:83]
	global_load_dwordx4 v[16:19], v73, s[82:83]
	global_load_dwordx4 v[20:23], v74, s[82:83]
	global_load_dwordx4 v[24:27], v75, s[82:83]
	global_load_dwordx4 v[28:31], v76, s[82:83]
	global_load_dwordx4 v[32:35], v182, s[82:83]
	s_waitcnt vmcnt(16)
	s_branch .Ltr_pr1_t1wa

; #define LAS __attribute__((address_space(3)))
; __device__ __forceinline__ unsigned cvtpk(float lo, float hi) { f32x2_t v = {lo, hi}; bf16x2_t b = __builtin_convertvector(v, bf16x2_t); return __builtin_bit_cast(unsigned, b); }
; template <int MODE>
; __device__ __forceinline__ void transpose_item(const float* W, int N, bf16_t* WT, int ldt, int coff, LAS float* scr, int item, int lane, const float* g) {
;     const int nblk = N / 32, kb = item / nblk, nb = item % nblk, k0 = 64 * kb, n0 = 32 * nb;
; #pragma unroll 8
;     for (int i = 0; i < 32; ++i) { const int kk = 2 * i + (lane >> 5); float v = W[(size_t)(k0 + kk) * N + n0 + (lane & 31)]; if (MODE >= 1) v *= g[k0 + kk]; scr[kk * 33 + (lane & 31)] = v; }
;     asm volatile("s_waitcnt lgkmcnt(0)" ::: "memory");
;     const int c = lane & 7;
; #pragma unroll
;     for (int j = 0; j < 4; ++j) {
;         const int n = (lane >> 3) + 8 * j; const LAS float* s = scr + (8 * c) * 33 + n;
;         u32x4 o; o.x = cvtpk(s[0 * 33], s[1 * 33]); o.y = cvtpk(s[2 * 33], s[3 * 33]); o.z = cvtpk(s[4 * 33], s[5 * 33]); o.w = cvtpk(s[6 * 33], s[7 * 33]);
;         int dr = n0 + n;
;         if (MODE == 1) { dr = (dr < DFF) ? 256 * (dr >> 7) + (dr & 127) : 256 * ((dr - DFF) >> 7) + 128 + ((dr - DFF) & 127); }
;         if (MODE == 2) {
;             if (dr >= 6144) { const int t = dr - 6144, ch = t & 2047; dr = 6144 + 256 * (ch >> 7) + ((t >> 11) << 7) + (ch & 127); }
;             else if (dr >= 4096) { const int t = dr - 4096, ch = t & 1023; dr = 4096 + 256 * (ch >> 7) + ((t >> 10) << 7) + (ch & 127); }
;         }
;         *(u32x4*)(WT + (size_t)dr * ldt + coff + k0 + 8 * c) = o;
;     }
;     asm volatile("s_waitcnt lgkmcnt(0)" ::: "memory");
; }
.Ltr_pr1_t1wa:
	s_add_u32 s79, s79, 0x300
	s_lshr_b32 s86, s81, 6
	s_and_b32 s87, s81, 0x3f
	s_mul_i32 s88, s87, 0x20000
	s_lshl_b32 s86, s86, 7
	s_add_u32 s88, s88, s86
	s_add_u32 s84, s36, s88
	s_addc_u32 s85, s37, 0
	ds_write_b32 v188, v40 offset:0
	ds_write_b32 v188, v41 offset:4
	ds_write_b32 v188, v42 offset:8
	ds_write_b32 v188, v43 offset:12
	ds_write_b32 v188, v44 offset:1056
	ds_write_b32 v188, v45 offset:1060
	ds_write_b32 v188, v46 offset:1064
	ds_write_b32 v188, v47 offset:1068
	ds_write_b32 v188, v48 offset:2112
	ds_write_b32 v188, v49 offset:2116
	ds_write_b32 v188, v50 offset:2120
	ds_write_b32 v188, v51 offset:2124
	ds_write_b32 v188, v52 offset:3168
	ds_write_b32 v188, v53 offset:3172
	ds_write_b32 v188, v54 offset:3176
	ds_write_b32 v188, v55 offset:3180
	ds_write_b32 v188, v56 offset:4224
	ds_write_b32 v188, v57 offset:4228
	ds_write_b32 v188, v58 offset:4232
	ds_write_b32 v188, v59 offset:4236
	ds_write_b32 v188, v60 offset:5280
	ds_write_b32 v188, v61 offset:5284
	ds_write_b32 v188, v62 offset:5288
	ds_write_b32 v188, v63 offset:5292
	ds_write_b32 v188, v64 offset:6336
	ds_write_b32 v188, v65 offset:6340
	ds_write_b32 v188, v66 offset:6344
	ds_write_b32 v188, v67 offset:6348
	ds_write_b32 v188, v68 offset:7392
	ds_write_b32 v188, v69 offset:7396
	ds_write_b32 v188, v70 offset:7400
	ds_write_b32 v188, v71 offset:7404
	s_waitcnt lgkmcnt(0)
	ds_read2_b32 v[128:129], v189 offset0:0 offset1:8
	ds_read2_b32 v[132:133], v189 offset0:33 offset1:41
	ds_read2_b32 v[136:137], v189 offset0:66 offset1:74
	ds_read2_b32 v[140:141], v189 offset0:99 offset1:107
	ds_read2_b32 v[144:145], v189 offset0:132 offset1:140
	ds_read2_b32 v[148:149], v189 offset0:165 offset1:173
	ds_read2_b32 v[152:153], v189 offset0:198 offset1:206
	ds_read2_b32 v[156:157], v189 offset0:231 offset1:239
	ds_read2_b32 v[130:131], v189 offset0:16 offset1:24
	ds_read2_b32 v[134:135], v189 offset0:49 offset1:57
	ds_read2_b32 v[138:139], v189 offset0:82 offset1:90
	ds_read2_b32 v[142:143], v189 offset0:115 offset1:123
	ds_read2_b32 v[146:147], v189 offset0:148 offset1:156
	ds_read2_b32 v[150:151], v189 offset0:181 offset1:189
	ds_read2_b32 v[154:155], v189 offset0:214 offset1:222
	ds_read2_b32 v[158:159], v189 offset0:247 offset1:255
	s_waitcnt lgkmcnt(0)
	v_cvt_pk_bf16_f32 v204, v128, v132
	v_cvt_pk_bf16_f32 v205, v136, v140
	v_cvt_pk_bf16_f32 v206, v144, v148
	v_cvt_pk_bf16_f32 v207, v152, v156
	global_store_dwordx4 v183, v[204:207], s[84:85]
	v_cvt_pk_bf16_f32 v208, v129, v133
	v_cvt_pk_bf16_f32 v209, v137, v141
	v_cvt_pk_bf16_f32 v210, v145, v149
	v_cvt_pk_bf16_f32 v211, v153, v157
	global_store_dwordx4 v184, v[208:211], s[84:85]
	v_cvt_pk_bf16_f32 v212, v130, v134
	v_cvt_pk_bf16_f32 v213, v138, v142
	v_cvt_pk_bf16_f32 v214, v146, v150
	v_cvt_pk_bf16_f32 v215, v154, v158
	global_store_dwordx4 v185, v[212:215], s[84:85]
	v_cvt_pk_bf16_f32 v216, v131, v135
	v_cvt_pk_bf16_f32 v217, v139, v143
	v_cvt_pk_bf16_f32 v218, v147, v151
	v_cvt_pk_bf16_f32 v219, v155, v159
	global_store_dwordx4 v186, v[216:219], s[84:85]
	s_add_u32 s81, s81, 0x300
	s_cmp_lt_u32 s81, 0x400
	s_cbranch_scc0 .Ltr_done_t1wa
.Ltr_st2_t1wa:
	s_cmp_lt_u32 s79, 0x400
	s_cbranch_scc0 .Ltr_nl2_t1wa
	s_lshr_b32 s86, s79, 6
	s_and_b32 s87, s79, 0x3f
	s_mul_i32 s88, s86, 0x80000
	s_lshl_b32 s87, s87, 7
	s_add_u32 s88, s88, s87
	s_add_u32 s82, s4, s88
	s_addc_u32 s83, s5, 0
	global_load_dwordx4 v[40:43], v36, s[82:83]
	global_load_dwordx4 v[44:47], v37, s[82:83]
	global_load_dwordx4 v[48:51], v72, s[82:83]
	global_load_dwordx4 v[52:55], v73, s[82:83]
	global_load_dwordx4 v[56:59], v74, s[82:83]
	global_load_dwordx4 v[60:63], v75, s[82:83]
	global_load_dwordx4 v[64:67], v76, s[82:83]
	global_load_dwordx4 v[68:71], v182, s[82:83]
	s_waitcnt vmcnt(16)
	s_branch .Ltr_pr2_t1wa

; #define LAS __attribute__((address_space(3)))
; __device__ __forceinline__ unsigned cvtpk(float lo, float hi) { f32x2_t v = {lo, hi}; bf16x2_t b = __builtin_convertvector(v, bf16x2_t); return __builtin_bit_cast(unsigned, b); }
; template <int MODE>
; __device__ __forceinline__ void transpose_item(const float* W, int N, bf16_t* WT, int ldt, int coff, LAS float* scr, int item, int lane, const float* g) {
;     const int nblk = N / 32, kb = item / nblk, nb = item % nblk, k0 = 64 * kb, n0 = 32 * nb;
; #pragma unroll 8
;     for (int i = 0; i < 32; ++i) { const int kk = 2 * i + (lane >> 5); float v = W[(size_t)(k0 + kk) * N + n0 + (lane & 31)]; if (MODE >= 1) v *= g[k0 + kk]; scr[kk * 33 + (lane & 31)] = v; }
;     asm volatile("s_waitcnt lgkmcnt(0)" ::: "memory");
;     const int c = lane & 7;
; #pragma unroll
;     for (int j = 0; j < 4; ++j) {
;         const int n = (lane >> 3) + 8 * j; const LAS float* s = scr + (8 * c) * 33 + n;
;         u32x4 o; o.x = cvtpk(s[0 * 33], s[1 * 33]); o.y = cvtpk(s[2 * 33], s[3 * 33]); o.z = cvtpk(s[4 * 33], s[5 * 33]); o.w = cvtpk(s[6 * 33], s[7 * 33]);
;         int dr = n0 + n;
;         if (MODE == 1) { dr = (dr < DFF) ? 256 * (dr >> 7) + (dr & 127) : 256 * ((dr - DFF) >> 7) + 128 + ((dr - DFF) & 127); }
;         if (MODE == 2) {
;             if (dr >= 6144) { const int t = dr - 6144, ch = t & 2047; dr = 6144 + 256 * (ch >> 7) + ((t >> 11) << 7) + (ch & 127); }
;             else if (dr >= 4096) { const int t = dr - 4096, ch = t & 1023; dr = 4096 + 256 * (ch >> 7) + ((t >> 10) << 7) + (ch & 127); }
;         }
;         *(u32x4*)(WT + (size_t)dr * ldt + coff + k0 + 8 * c) = o;
;     }
;     asm volatile("s_waitcnt lgkmcnt(0)" ::: "memory");
; }
; __global__ void __launch_bounds__(512, 2) mk_fwd(Args a) {
;     ...
;             if (r < I_A) { transpose_item<0>(a.in[I_WB], DM, WAB, 2048, 1024, scr, r, lane, nullptr); continue; } r -= I_A;
.Ltr_pr2_t1wa:
	s_add_u32 s79, s79, 0x300
	s_lshr_b32 s86, s81, 6
	s_and_b32 s87, s81, 0x3f
	s_mul_i32 s88, s87, 0x20000
	s_lshl_b32 s86, s86, 7
	s_add_u32 s88, s88, s86
	s_add_u32 s84, s36, s88
	s_addc_u32 s85, s37, 0
	ds_write_b32 v188, v96 offset:0
	ds_write_b32 v188, v97 offset:4
	ds_write_b32 v188, v98 offset:8
	ds_write_b32 v188, v99 offset:12
	ds_write_b32 v188, v100 offset:1056
	ds_write_b32 v188, v101 offset:1060
	ds_write_b32 v188, v102 offset:1064
	ds_write_b32 v188, v103 offset:1068
	ds_write_b32 v188, v104 offset:2112
	ds_write_b32 v188, v105 offset:2116
	ds_write_b32 v188, v106 offset:2120
	ds_write_b32 v188, v107 offset:2124
	ds_write_b32 v188, v108 offset:3168
	ds_write_b32 v188, v109 offset:3172
	ds_write_b32 v188, v110 offset:3176
	ds_write_b32 v188, v111 offset:3180
	ds_write_b32 v188, v112 offset:4224
	ds_write_b32 v188, v113 offset:4228
	ds_write_b32 v188, v114 offset:4232
	ds_write_b32 v188, v115 offset:4236
	ds_write_b32 v188, v116 offset:5280
	ds_write_b32 v188, v117 offset:5284
	ds_write_b32 v188, v118 offset:5288
	ds_write_b32 v188, v119 offset:5292
	ds_write_b32 v188, v120 offset:6336
	ds_write_b32 v188, v121 offset:6340
	ds_write_b32 v188, v122 offset:6344
	ds_write_b32 v188, v123 offset:6348
	ds_write_b32 v188, v124 offset:7392
	ds_write_b32 v188, v125 offset:7396
	ds_write_b32 v188, v126 offset:7400
	ds_write_b32 v188, v127 offset:7404
	s_waitcnt lgkmcnt(0)
	ds_read2_b32 v[128:129], v189 offset0:0 offset1:8
	ds_read2_b32 v[132:133], v189 offset0:33 offset1:41
	ds_read2_b32 v[136:137], v189 offset0:66 offset1:74
	ds_read2_b32 v[140:141], v189 offset0:99 offset1:107
	ds_read2_b32 v[144:145], v189 offset0:132 offset1:140
	ds_read2_b32 v[148:149], v189 offset0:165 offset1:173
	ds_read2_b32 v[152:153], v189 offset0:198 offset1:206
	ds_read2_b32 v[156:157], v189 offset0:231 offset1:239
	ds_read2_b32 v[130:131], v189 offset0:16 offset1:24
	ds_read2_b32 v[134:135], v189 offset0:49 offset1:57
	ds_read2_b32 v[138:139], v189 offset0:82 offset1:90
	ds_read2_b32 v[142:143], v189 offset0:115 offset1:123
	ds_read2_b32 v[146:147], v189 offset0:148 offset1:156
	ds_read2_b32 v[150:151], v189 offset0:181 offset1:189
	ds_read2_b32 v[154:155], v189 offset0:214 offset1:222
	ds_read2_b32 v[158:159], v189 offset0:247 offset1:255
	s_waitcnt lgkmcnt(0)
	v_cvt_pk_bf16_f32 v204, v128, v132
	v_cvt_pk_bf16_f32 v205, v136, v140
	v_cvt_pk_bf16_f32 v206, v144, v148
	v_cvt_pk_bf16_f32 v207, v152, v156
	global_store_dwordx4 v183, v[204:207], s[84:85]
	v_cvt_pk_bf16_f32 v208, v129, v133
	v_cvt_pk_bf16_f32 v209, v137, v141
	v_cvt_pk_bf16_f32 v210, v145, v149
	v_cvt_pk_bf16_f32 v211, v153, v157
	global_store_dwordx4 v184, v[208:211], s[84:85]
	v_cvt_pk_bf16_f32 v212, v130, v134
	v_cvt_pk_bf16_f32 v213, v138, v142
	v_cvt_pk_bf16_f32 v214, v146, v150
	v_cvt_pk_bf16_f32 v215, v154, v158
	global_store_dwordx4 v185, v[212:215], s[84:85]
	v_cvt_pk_bf16_f32 v216, v131, v135
	v_cvt_pk_bf16_f32 v217, v139, v143
	v_cvt_pk_bf16_f32 v218, v147, v151
	v_cvt_pk_bf16_f32 v219, v155, v159
	global_store_dwordx4 v186, v[216:219], s[84:85]
	s_add_u32 s81, s81, 0x300
	s_cmp_lt_u32 s81, 0x400
	s_cbranch_scc0 .Ltr_done_t1wa
	s_branch .Ltr_st0_t1wa
.Ltr_done_t1wa:
	s_add_u32 s78, s67, 0x100
	s_cmp_ge_u32 s78, 0x300
	s_cselect_b32 s79, 0x300, 0
	s_sub_u32 s78, s78, s79
	s_cmp_lt_u32 s78, 0x400
	s_cbranch_scc0 .Ltr_done_t1wb
	v_lshrrev_b32_e32 v0, 3, v220
	v_and_b32_e32 v1, 7, v220
	v_mul_u32_u24_e32 v2, 0x2000, v0
	v_lshl_add_u32 v36, v1, 4, v2
	v_add_u32_e32 v37, 0x10000, v36
	v_add_u32_e32 v72, 0x20000, v36
	v_add_u32_e32 v73, 0x30000, v36
	v_add_u32_e32 v74, 0x40000, v36
	v_add_u32_e32 v75, 0x50000, v36
	v_add_u32_e32 v76, 0x60000, v36
	v_add_u32_e32 v182, 0x70000, v36
	v_mul_u32_u24_e32 v2, 0x84, v0
	v_lshl_add_u32 v2, v1, 4, v2
	v_add_u32_e32 v188, s32, v2
	v_mul_u32_u24_e32 v2, 0x420, v1
	v_lshl_add_u32 v2, v0, 2, v2
	v_add_u32_e32 v189, s32, v2
	v_mul_u32_u24_e32 v2, 0x1000, v0
	v_lshl_add_u32 v183, v1, 4, v2
	v_add_u32_e32 v184, 0x8000, v183
	v_add_u32_e32 v185, 0x10000, v183
	v_add_u32_e32 v186, 0x18000, v183
	s_mov_b32 s81, s78
	s_mov_b32 s79, s78
	s_lshr_b32 s86, s79, 6
	s_and_b32 s87, s79, 0x3f
	s_mul_i32 s88, s86, 0x80000
	s_lshl_b32 s87, s87, 7
	s_add_u32 s88, s88, s87
	s_add_u32 s82, s6, s88
	s_addc_u32 s83, s7, 0
	global_load_dwordx4 v[4:7], v36, s[82:83]
	global_load_dwordx4 v[8:11], v37, s[82:83]
	global_load_dwordx4 v[12:15], v72, s[82:83]
	global_load_dwordx4 v[16:19], v73, s[82:83]
	global_load_dwordx4 v[20:23], v74, s[82:83]
	global_load_dwordx4 v[24:27], v75, s[82:83]
	global_load_dwordx4 v[28:31], v76, s[82:83]
	global_load_dwordx4 v[32:35], v182, s[82:83]
	s_add_u32 s79, s79, 0x300
	s_cmp_lt_u32 s79, 0x400
	s_cbranch_scc0 .Ltr_p1_t1wb
	s_lshr_b32 s86, s79, 6
	s_and_b32 s87, s79, 0x3f
	s_mul_i32 s88, s86, 0x80000
	s_lshl_b32 s87, s87, 7
	s_add_u32 s88, s88, s87
	s_add_u32 s82, s6, s88
	s_addc_u32 s83, s7, 0
	global_load_dwordx4 v[40:43], v36, s[82:83]
	global_load_dwordx4 v[44:47], v37, s[82:83]
	global_load_dwordx4 v[48:51], v72, s[82:83]
	global_load_dwordx4 v[52:55], v73, s[82:83]
	global_load_dwordx4 v[56:59], v74, s[82:83]
	global_load_dwordx4 v[60:63], v75, s[82:83]
	global_load_dwordx4 v[64:67], v76, s[82:83]
	global_load_dwordx4 v[68:71], v182, s[82:83]

; #define LAS __attribute__((address_space(3)))
; __device__ __forceinline__ unsigned cvtpk(float lo, float hi) { f32x2_t v = {lo, hi}; bf16x2_t b = __builtin_convertvector(v, bf16x2_t); return __builtin_bit_cast(unsigned, b); }
; template <int MODE>
; __device__ __forceinline__ void transpose_item(const float* W, int N, bf16_t* WT, int ldt, int coff, LAS float* scr, int item, int lane, const float* g) {
;     const int nblk = N / 32, kb = item / nblk, nb = item % nblk, k0 = 64 * kb, n0 = 32 * nb;
; #pragma unroll 8
;     for (int i = 0; i < 32; ++i) { const int kk = 2 * i + (lane >> 5); float v = W[(size_t)(k0 + kk) * N + n0 + (lane & 31)]; if (MODE >= 1) v *= g[k0 + kk]; scr[kk * 33 + (lane & 31)] = v; }
;     asm volatile("s_waitcnt lgkmcnt(0)" ::: "memory");
;     const int c = lane & 7;
; #pragma unroll
;     for (int j = 0; j < 4; ++j) {
;         const int n = (lane >> 3) + 8 * j; const LAS float* s = scr + (8 * c) * 33 + n;
;         u32x4 o; o.x = cvtpk(s[0 * 33], s[1 * 33]); o.y = cvtpk(s[2 * 33], s[3 * 33]); o.z = cvtpk(s[4 * 33], s[5 * 33]); o.w = cvtpk(s[6 * 33], s[7 * 33]);
;         int dr = n0 + n;
;         if (MODE == 1) { dr = (dr < DFF) ? 256 * (dr >> 7) + (dr & 127) : 256 * ((dr - DFF) >> 7) + 128 + ((dr - DFF) & 127); }
;         if (MODE == 2) {
;             if (dr >= 6144) { const int t = dr - 6144, ch = t & 2047; dr = 6144 + 256 * (ch >> 7) + ((t >> 11) << 7) + (ch & 127); }
;             else if (dr >= 4096) { const int t = dr - 4096, ch = t & 1023; dr = 4096 + 256 * (ch >> 7) + ((t >> 10) << 7) + (ch & 127); }
;         }
;         *(u32x4*)(WT + (size_t)dr * ldt + coff + k0 + 8 * c) = o;
;     }
;     asm volatile("s_waitcnt lgkmcnt(0)" ::: "memory");
; }
.Ltr_st0_t1wb:
	s_cmp_lt_u32 s79, 0x400
	s_cbranch_scc0 .Ltr_nl0_t1wb
	s_lshr_b32 s86, s79, 6
	s_and_b32 s87, s79, 0x3f
	s_mul_i32 s88, s86, 0x80000
	s_lshl_b32 s87, s87, 7
	s_add_u32 s88, s88, s87
	s_add_u32 s82, s6, s88
	s_addc_u32 s83, s7, 0
	global_load_dwordx4 v[96:99], v36, s[82:83]
	global_load_dwordx4 v[100:103], v37, s[82:83]
	global_load_dwordx4 v[104:107], v72, s[82:83]
	global_load_dwordx4 v[108:111], v73, s[82:83]
	global_load_dwordx4 v[112:115], v74, s[82:83]
	global_load_dwordx4 v[116:119], v75, s[82:83]
	global_load_dwordx4 v[120:123], v76, s[82:83]
	global_load_dwordx4 v[124:127], v182, s[82:83]
	s_waitcnt vmcnt(16)
	s_branch .Ltr_pr0_t1wb

; #define LAS __attribute__((address_space(3)))
; __device__ __forceinline__ unsigned cvtpk(float lo, float hi) { f32x2_t v = {lo, hi}; bf16x2_t b = __builtin_convertvector(v, bf16x2_t); return __builtin_bit_cast(unsigned, b); }
; template <int MODE>
; __device__ __forceinline__ void transpose_item(const float* W, int N, bf16_t* WT, int ldt, int coff, LAS float* scr, int item, int lane, const float* g) {
;     const int nblk = N / 32, kb = item / nblk, nb = item % nblk, k0 = 64 * kb, n0 = 32 * nb;
; #pragma unroll 8
;     for (int i = 0; i < 32; ++i) { const int kk = 2 * i + (lane >> 5); float v = W[(size_t)(k0 + kk) * N + n0 + (lane & 31)]; if (MODE >= 1) v *= g[k0 + kk]; scr[kk * 33 + (lane & 31)] = v; }
;     asm volatile("s_waitcnt lgkmcnt(0)" ::: "memory");
;     const int c = lane & 7;
; #pragma unroll
;     for (int j = 0; j < 4; ++j) {
;         const int n = (lane >> 3) + 8 * j; const LAS float* s = scr + (8 * c) * 33 + n;
;         u32x4 o; o.x = cvtpk(s[0 * 33], s[1 * 33]); o.y = cvtpk(s[2 * 33], s[3 * 33]); o.z = cvtpk(s[4 * 33], s[5 * 33]); o.w = cvtpk(s[6 * 33], s[7 * 33]);
;         int dr = n0 + n;
;         if (MODE == 1) { dr = (dr < DFF) ? 256 * (dr >> 7) + (dr & 127) : 256 * ((dr - DFF) >> 7) + 128 + ((dr - DFF) & 127); }
;         if (MODE == 2) {
;             if (dr >= 6144) { const int t = dr - 6144, ch = t & 2047; dr = 6144 + 256 * (ch >> 7) + ((t >> 11) << 7) + (ch & 127); }
;             else if (dr >= 4096) { const int t = dr - 4096, ch = t & 1023; dr = 4096 + 256 * (ch >> 7) + ((t >> 10) << 7) + (ch & 127); }
;         }
;         *(u32x4*)(WT + (size_t)dr * ldt + coff + k0 + 8 * c) = o;
;     }
;     asm volatile("s_waitcnt lgkmcnt(0)" ::: "memory");
; }
.Ltr_pr0_t1wb:
	s_add_u32 s79, s79, 0x300
	s_lshr_b32 s86, s81, 6
	s_and_b32 s87, s81, 0x3f
	s_mul_i32 s88, s87, 0x20000
	s_lshl_b32 s86, s86, 7
	s_add_u32 s88, s88, s86
	s_add_u32 s84, s40, s88
	s_addc_u32 s85, s41, 0
	ds_write_b32 v188, v4 offset:0
	ds_write_b32 v188, v5 offset:4
	ds_write_b32 v188, v6 offset:8
	ds_write_b32 v188, v7 offset:12
	ds_write_b32 v188, v8 offset:1056
	ds_write_b32 v188, v9 offset:1060
	ds_write_b32 v188, v10 offset:1064
	ds_write_b32 v188, v11 offset:1068
	ds_write_b32 v188, v12 offset:2112
	ds_write_b32 v188, v13 offset:2116
	ds_write_b32 v188, v14 offset:2120
	ds_write_b32 v188, v15 offset:2124
	ds_write_b32 v188, v16 offset:3168
	ds_write_b32 v188, v17 offset:3172
	ds_write_b32 v188, v18 offset:3176
	ds_write_b32 v188, v19 offset:3180
	ds_write_b32 v188, v20 offset:4224
	ds_write_b32 v188, v21 offset:4228
	ds_write_b32 v188, v22 offset:4232
	ds_write_b32 v188, v23 offset:4236
	ds_write_b32 v188, v24 offset:5280
	ds_write_b32 v188, v25 offset:5284
	ds_write_b32 v188, v26 offset:5288
	ds_write_b32 v188, v27 offset:5292
	ds_write_b32 v188, v28 offset:6336
	ds_write_b32 v188, v29 offset:6340
	ds_write_b32 v188, v30 offset:6344
	ds_write_b32 v188, v31 offset:6348
	ds_write_b32 v188, v32 offset:7392
	ds_write_b32 v188, v33 offset:7396
	ds_write_b32 v188, v34 offset:7400
	ds_write_b32 v188, v35 offset:7404
	s_waitcnt lgkmcnt(0)
	ds_read2_b32 v[128:129], v189 offset0:0 offset1:8
	ds_read2_b32 v[132:133], v189 offset0:33 offset1:41
	ds_read2_b32 v[136:137], v189 offset0:66 offset1:74
	ds_read2_b32 v[140:141], v189 offset0:99 offset1:107
	ds_read2_b32 v[144:145], v189 offset0:132 offset1:140
	ds_read2_b32 v[148:149], v189 offset0:165 offset1:173
	ds_read2_b32 v[152:153], v189 offset0:198 offset1:206
	ds_read2_b32 v[156:157], v189 offset0:231 offset1:239
	ds_read2_b32 v[130:131], v189 offset0:16 offset1:24
	ds_read2_b32 v[134:135], v189 offset0:49 offset1:57
	ds_read2_b32 v[138:139], v189 offset0:82 offset1:90
	ds_read2_b32 v[142:143], v189 offset0:115 offset1:123
	ds_read2_b32 v[146:147], v189 offset0:148 offset1:156
	ds_read2_b32 v[150:151], v189 offset0:181 offset1:189
	ds_read2_b32 v[154:155], v189 offset0:214 offset1:222
	ds_read2_b32 v[158:159], v189 offset0:247 offset1:255
	s_waitcnt lgkmcnt(0)
	v_cvt_pk_bf16_f32 v204, v128, v132
	v_cvt_pk_bf16_f32 v205, v136, v140
	v_cvt_pk_bf16_f32 v206, v144, v148
	v_cvt_pk_bf16_f32 v207, v152, v156
	global_store_dwordx4 v183, v[204:207], s[84:85]
	v_cvt_pk_bf16_f32 v208, v129, v133
	v_cvt_pk_bf16_f32 v209, v137, v141
	v_cvt_pk_bf16_f32 v210, v145, v149
	v_cvt_pk_bf16_f32 v211, v153, v157
	global_store_dwordx4 v184, v[208:211], s[84:85]
	v_cvt_pk_bf16_f32 v212, v130, v134
	v_cvt_pk_bf16_f32 v213, v138, v142
	v_cvt_pk_bf16_f32 v214, v146, v150
	v_cvt_pk_bf16_f32 v215, v154, v158
	global_store_dwordx4 v185, v[212:215], s[84:85]
	v_cvt_pk_bf16_f32 v216, v131, v135
	v_cvt_pk_bf16_f32 v217, v139, v143
	v_cvt_pk_bf16_f32 v218, v147, v151
	v_cvt_pk_bf16_f32 v219, v155, v159
	global_store_dwordx4 v186, v[216:219], s[84:85]
	s_add_u32 s81, s81, 0x300
	s_cmp_lt_u32 s81, 0x400
	s_cbranch_scc0 .Ltr_done_t1wb
.Ltr_st1_t1wb:
	s_cmp_lt_u32 s79, 0x400
	s_cbranch_scc0 .Ltr_nl1_t1wb
	s_lshr_b32 s86, s79, 6
	s_and_b32 s87, s79, 0x3f
	s_mul_i32 s88, s86, 0x80000
	s_lshl_b32 s87, s87, 7
	s_add_u32 s88, s88, s87
	s_add_u32 s82, s6, s88
	s_addc_u32 s83, s7, 0
	global_load_dwordx4 v[4:7], v36, s[82:83]
	global_load_dwordx4 v[8:11], v37, s[82:83]
	global_load_dwordx4 v[12:15], v72, s[82:83]
	global_load_dwordx4 v[16:19], v73, s[82:83]
	global_load_dwordx4 v[20:23], v74, s[82:83]
	global_load_dwordx4 v[24:27], v75, s[82:83]
	global_load_dwordx4 v[28:31], v76, s[82:83]
	global_load_dwordx4 v[32:35], v182, s[82:83]
	s_waitcnt vmcnt(16)
	s_branch .Ltr_pr1_t1wb

; #define LAS __attribute__((address_space(3)))
; __device__ __forceinline__ unsigned cvtpk(float lo, float hi) { f32x2_t v = {lo, hi}; bf16x2_t b = __builtin_convertvector(v, bf16x2_t); return __builtin_bit_cast(unsigned, b); }
; template <int MODE>
; __device__ __forceinline__ void transpose_item(const float* W, int N, bf16_t* WT, int ldt, int coff, LAS float* scr, int item, int lane, const float* g) {
;     const int nblk = N / 32, kb = item / nblk, nb = item % nblk, k0 = 64 * kb, n0 = 32 * nb;
; #pragma unroll 8
;     for (int i = 0; i < 32; ++i) { const int kk = 2 * i + (lane >> 5); float v = W[(size_t)(k0 + kk) * N + n0 + (lane & 31)]; if (MODE >= 1) v *= g[k0 + kk]; scr[kk * 33 + (lane & 31)] = v; }
;     asm volatile("s_waitcnt lgkmcnt(0)" ::: "memory");
;     const int c = lane & 7;
; #pragma unroll
;     for (int j = 0; j < 4; ++j) {
;         const int n = (lane >> 3) + 8 * j; const LAS float* s = scr + (8 * c) * 33 + n;
;         u32x4 o; o.x = cvtpk(s[0 * 33], s[1 * 33]); o.y = cvtpk(s[2 * 33], s[3 * 33]); o.z = cvtpk(s[4 * 33], s[5 * 33]); o.w = cvtpk(s[6 * 33], s[7 * 33]);
;         int dr = n0 + n;
;         if (MODE == 1) { dr = (dr < DFF) ? 256 * (dr >> 7) + (dr & 127) : 256 * ((dr - DFF) >> 7) + 128 + ((dr - DFF) & 127); }
;         if (MODE == 2) {
;             if (dr >= 6144) { const int t = dr - 6144, ch = t & 2047; dr = 6144 + 256 * (ch >> 7) + ((t >> 11) << 7) + (ch & 127); }
;             else if (dr >= 4096) { const int t = dr - 4096, ch = t & 1023; dr = 4096 + 256 * (ch >> 7) + ((t >> 10) << 7) + (ch & 127); }
;         }
;         *(u32x4*)(WT + (size_t)dr * ldt + coff + k0 + 8 * c) = o;
;     }
;     asm volatile("s_waitcnt lgkmcnt(0)" ::: "memory");
; }
.Ltr_pr1_t1wb:
	s_add_u32 s79, s79, 0x300
	s_lshr_b32 s86, s81, 6
	s_and_b32 s87, s81, 0x3f
	s_mul_i32 s88, s87, 0x20000
	s_lshl_b32 s86, s86, 7
	s_add_u32 s88, s88, s86
	s_add_u32 s84, s40, s88
	s_addc_u32 s85, s41, 0
	ds_write_b32 v188, v40 offset:0
	ds_write_b32 v188, v41 offset:4
	ds_write_b32 v188, v42 offset:8
	ds_write_b32 v188, v43 offset:12
	ds_write_b32 v188, v44 offset:1056
	ds_write_b32 v188, v45 offset:1060
	ds_write_b32 v188, v46 offset:1064
	ds_write_b32 v188, v47 offset:1068
	ds_write_b32 v188, v48 offset:2112
	ds_write_b32 v188, v49 offset:2116
	ds_write_b32 v188, v50 offset:2120
	ds_write_b32 v188, v51 offset:2124
	ds_write_b32 v188, v52 offset:3168
	ds_write_b32 v188, v53 offset:3172
	ds_write_b32 v188, v54 offset:3176
	ds_write_b32 v188, v55 offset:3180
	ds_write_b32 v188, v56 offset:4224
	ds_write_b32 v188, v57 offset:4228
	ds_write_b32 v188, v58 offset:4232
	ds_write_b32 v188, v59 offset:4236
	ds_write_b32 v188, v60 offset:5280
	ds_write_b32 v188, v61 offset:5284
	ds_write_b32 v188, v62 offset:5288
	ds_write_b32 v188, v63 offset:5292
	ds_write_b32 v188, v64 offset:6336
	ds_write_b32 v188, v65 offset:6340
	ds_write_b32 v188, v66 offset:6344
	ds_write_b32 v188, v67 offset:6348
	ds_write_b32 v188, v68 offset:7392
	ds_write_b32 v188, v69 offset:7396
	ds_write_b32 v188, v70 offset:7400
	ds_write_b32 v188, v71 offset:7404
	s_waitcnt lgkmcnt(0)
	ds_read2_b32 v[128:129], v189 offset0:0 offset1:8
	ds_read2_b32 v[132:133], v189 offset0:33 offset1:41
	ds_read2_b32 v[136:137], v189 offset0:66 offset1:74
	ds_read2_b32 v[140:141], v189 offset0:99 offset1:107
	ds_read2_b32 v[144:145], v189 offset0:132 offset1:140
	ds_read2_b32 v[148:149], v189 offset0:165 offset1:173
	ds_read2_b32 v[152:153], v189 offset0:198 offset1:206
	ds_read2_b32 v[156:157], v189 offset0:231 offset1:239
	ds_read2_b32 v[130:131], v189 offset0:16 offset1:24
	ds_read2_b32 v[134:135], v189 offset0:49 offset1:57
	ds_read2_b32 v[138:139], v189 offset0:82 offset1:90
	ds_read2_b32 v[142:143], v189 offset0:115 offset1:123
	ds_read2_b32 v[146:147], v189 offset0:148 offset1:156
	ds_read2_b32 v[150:151], v189 offset0:181 offset1:189
	ds_read2_b32 v[154:155], v189 offset0:214 offset1:222
	ds_read2_b32 v[158:159], v189 offset0:247 offset1:255
	s_waitcnt lgkmcnt(0)
	v_cvt_pk_bf16_f32 v204, v128, v132
	v_cvt_pk_bf16_f32 v205, v136, v140
	v_cvt_pk_bf16_f32 v206, v144, v148
	v_cvt_pk_bf16_f32 v207, v152, v156
	global_store_dwordx4 v183, v[204:207], s[84:85]
	v_cvt_pk_bf16_f32 v208, v129, v133
	v_cvt_pk_bf16_f32 v209, v137, v141
	v_cvt_pk_bf16_f32 v210, v145, v149
	v_cvt_pk_bf16_f32 v211, v153, v157
	global_store_dwordx4 v184, v[208:211], s[84:85]
	v_cvt_pk_bf16_f32 v212, v130, v134
	v_cvt_pk_bf16_f32 v213, v138, v142
	v_cvt_pk_bf16_f32 v214, v146, v150
	v_cvt_pk_bf16_f32 v215, v154, v158
	global_store_dwordx4 v185, v[212:215], s[84:85]
	v_cvt_pk_bf16_f32 v216, v131, v135
	v_cvt_pk_bf16_f32 v217, v139, v143
	v_cvt_pk_bf16_f32 v218, v147, v151
	v_cvt_pk_bf16_f32 v219, v155, v159
	global_store_dwordx4 v186, v[216:219], s[84:85]
	s_add_u32 s81, s81, 0x300
	s_cmp_lt_u32 s81, 0x400
	s_cbranch_scc0 .Ltr_done_t1wb
.Ltr_st2_t1wb:
	s_cmp_lt_u32 s79, 0x400
	s_cbranch_scc0 .Ltr_nl2_t1wb
	s_lshr_b32 s86, s79, 6
	s_and_b32 s87, s79, 0x3f
	s_mul_i32 s88, s86, 0x80000
	s_lshl_b32 s87, s87, 7
	s_add_u32 s88, s88, s87
	s_add_u32 s82, s6, s88
	s_addc_u32 s83, s7, 0
	global_load_dwordx4 v[40:43], v36, s[82:83]
	global_load_dwordx4 v[44:47], v37, s[82:83]
	global_load_dwordx4 v[48:51], v72, s[82:83]
	global_load_dwordx4 v[52:55], v73, s[82:83]
	global_load_dwordx4 v[56:59], v74, s[82:83]
	global_load_dwordx4 v[60:63], v75, s[82:83]
	global_load_dwordx4 v[64:67], v76, s[82:83]
	global_load_dwordx4 v[68:71], v182, s[82:83]
	s_waitcnt vmcnt(16)
	s_branch .Ltr_pr2_t1wb

; #define LAS __attribute__((address_space(3)))
; __device__ __forceinline__ unsigned cvtpk(float lo, float hi) { f32x2_t v = {lo, hi}; bf16x2_t b = __builtin_convertvector(v, bf16x2_t); return __builtin_bit_cast(unsigned, b); }
; template <int MODE>
; __device__ __forceinline__ void transpose_item(const float* W, int N, bf16_t* WT, int ldt, int coff, LAS float* scr, int item, int lane, const float* g) {
;     const int nblk = N / 32, kb = item / nblk, nb = item % nblk, k0 = 64 * kb, n0 = 32 * nb;
; #pragma unroll 8
;     for (int i = 0; i < 32; ++i) { const int kk = 2 * i + (lane >> 5); float v = W[(size_t)(k0 + kk) * N + n0 + (lane & 31)]; if (MODE >= 1) v *= g[k0 + kk]; scr[kk * 33 + (lane & 31)] = v; }
;     asm volatile("s_waitcnt lgkmcnt(0)" ::: "memory");
;     const int c = lane & 7;
; #pragma unroll
;     for (int j = 0; j < 4; ++j) {
;         const int n = (lane >> 3) + 8 * j; const LAS float* s = scr + (8 * c) * 33 + n;
;         u32x4 o; o.x = cvtpk(s[0 * 33], s[1 * 33]); o.y = cvtpk(s[2 * 33], s[3 * 33]); o.z = cvtpk(s[4 * 33], s[5 * 33]); o.w = cvtpk(s[6 * 33], s[7 * 33]);
;         int dr = n0 + n;
;         if (MODE == 1) { dr = (dr < DFF) ? 256 * (dr >> 7) + (dr & 127) : 256 * ((dr - DFF) >> 7) + 128 + ((dr - DFF) & 127); }
;         if (MODE == 2) {
;             if (dr >= 6144) { const int t = dr - 6144, ch = t & 2047; dr = 6144 + 256 * (ch >> 7) + ((t >> 11) << 7) + (ch & 127); }
;             else if (dr >= 4096) { const int t = dr - 4096, ch = t & 1023; dr = 4096 + 256 * (ch >> 7) + ((t >> 10) << 7) + (ch & 127); }
;         }
;         *(u32x4*)(WT + (size_t)dr * ldt + coff + k0 + 8 * c) = o;
;     }
;     asm volatile("s_waitcnt lgkmcnt(0)" ::: "memory");
; }
; __global__ void __launch_bounds__(512, 2) mk_fwd(Args a) {
;     ...
;             if (r < I_O) { transpose_item<0>(a.in[I_WO], DM, WO, DM, 0, scr, r, lane, nullptr); continue; } r -= I_O;
.Ltr_pr2_t1wb:
	s_add_u32 s79, s79, 0x300
	s_lshr_b32 s86, s81, 6
	s_and_b32 s87, s81, 0x3f
	s_mul_i32 s88, s87, 0x20000
	s_lshl_b32 s86, s86, 7
	s_add_u32 s88, s88, s86
	s_add_u32 s84, s40, s88
	s_addc_u32 s85, s41, 0
	ds_write_b32 v188, v96 offset:0
	ds_write_b32 v188, v97 offset:4
	ds_write_b32 v188, v98 offset:8
	ds_write_b32 v188, v99 offset:12
	ds_write_b32 v188, v100 offset:1056
	ds_write_b32 v188, v101 offset:1060
	ds_write_b32 v188, v102 offset:1064
	ds_write_b32 v188, v103 offset:1068
	ds_write_b32 v188, v104 offset:2112
	ds_write_b32 v188, v105 offset:2116
	ds_write_b32 v188, v106 offset:2120
	ds_write_b32 v188, v107 offset:2124
	ds_write_b32 v188, v108 offset:3168
	ds_write_b32 v188, v109 offset:3172
	ds_write_b32 v188, v110 offset:3176
	ds_write_b32 v188, v111 offset:3180
	ds_write_b32 v188, v112 offset:4224
	ds_write_b32 v188, v113 offset:4228
	ds_write_b32 v188, v114 offset:4232
	ds_write_b32 v188, v115 offset:4236
	ds_write_b32 v188, v116 offset:5280
	ds_write_b32 v188, v117 offset:5284
	ds_write_b32 v188, v118 offset:5288
	ds_write_b32 v188, v119 offset:5292
	ds_write_b32 v188, v120 offset:6336
	ds_write_b32 v188, v121 offset:6340
	ds_write_b32 v188, v122 offset:6344
	ds_write_b32 v188, v123 offset:6348
	ds_write_b32 v188, v124 offset:7392
	ds_write_b32 v188, v125 offset:7396
	ds_write_b32 v188, v126 offset:7400
	ds_write_b32 v188, v127 offset:7404
	s_waitcnt lgkmcnt(0)
	ds_read2_b32 v[128:129], v189 offset0:0 offset1:8
	ds_read2_b32 v[132:133], v189 offset0:33 offset1:41
	ds_read2_b32 v[136:137], v189 offset0:66 offset1:74
	ds_read2_b32 v[140:141], v189 offset0:99 offset1:107
	ds_read2_b32 v[144:145], v189 offset0:132 offset1:140
	ds_read2_b32 v[148:149], v189 offset0:165 offset1:173
	ds_read2_b32 v[152:153], v189 offset0:198 offset1:206
	ds_read2_b32 v[156:157], v189 offset0:231 offset1:239
	ds_read2_b32 v[130:131], v189 offset0:16 offset1:24
	ds_read2_b32 v[134:135], v189 offset0:49 offset1:57
	ds_read2_b32 v[138:139], v189 offset0:82 offset1:90
	ds_read2_b32 v[142:143], v189 offset0:115 offset1:123
	ds_read2_b32 v[146:147], v189 offset0:148 offset1:156
	ds_read2_b32 v[150:151], v189 offset0:181 offset1:189
	ds_read2_b32 v[154:155], v189 offset0:214 offset1:222
	ds_read2_b32 v[158:159], v189 offset0:247 offset1:255
	s_waitcnt lgkmcnt(0)
	v_cvt_pk_bf16_f32 v204, v128, v132
	v_cvt_pk_bf16_f32 v205, v136, v140
	v_cvt_pk_bf16_f32 v206, v144, v148
	v_cvt_pk_bf16_f32 v207, v152, v156
	global_store_dwordx4 v183, v[204:207], s[84:85]
	v_cvt_pk_bf16_f32 v208, v129, v133
	v_cvt_pk_bf16_f32 v209, v137, v141
	v_cvt_pk_bf16_f32 v210, v145, v149
	v_cvt_pk_bf16_f32 v211, v153, v157
	global_store_dwordx4 v184, v[208:211], s[84:85]
	v_cvt_pk_bf16_f32 v212, v130, v134
	v_cvt_pk_bf16_f32 v213, v138, v142
	v_cvt_pk_bf16_f32 v214, v146, v150
	v_cvt_pk_bf16_f32 v215, v154, v158
	global_store_dwordx4 v185, v[212:215], s[84:85]
	v_cvt_pk_bf16_f32 v216, v131, v135
	v_cvt_pk_bf16_f32 v217, v139, v143
	v_cvt_pk_bf16_f32 v218, v147, v151
	v_cvt_pk_bf16_f32 v219, v155, v159
	global_store_dwordx4 v186, v[216:219], s[84:85]
	s_add_u32 s81, s81, 0x300
	s_cmp_lt_u32 s81, 0x400
	s_cbranch_scc0 .Ltr_done_t1wb
	s_branch .Ltr_st0_t1wb
.Ltr_done_t1wb:
	s_add_u32 s78, s67, 0x200
	s_cmp_ge_u32 s78, 0x300
	s_cselect_b32 s79, 0x300, 0
	s_sub_u32 s78, s78, s79
	s_cmp_lt_u32 s78, 0x800
	s_cbranch_scc0 .Ltr_done_t1wo
	v_lshrrev_b32_e32 v0, 3, v220
	v_and_b32_e32 v1, 7, v220
	v_mul_u32_u24_e32 v2, 0x2000, v0
	v_lshl_add_u32 v36, v1, 4, v2
	v_add_u32_e32 v37, 0x10000, v36
	v_add_u32_e32 v72, 0x20000, v36
	v_add_u32_e32 v73, 0x30000, v36
	v_add_u32_e32 v74, 0x40000, v36
	v_add_u32_e32 v75, 0x50000, v36
	v_add_u32_e32 v76, 0x60000, v36
	v_add_u32_e32 v182, 0x70000, v36
	v_mul_u32_u24_e32 v2, 0x84, v0
	v_lshl_add_u32 v2, v1, 4, v2
	v_add_u32_e32 v188, s32, v2
	v_mul_u32_u24_e32 v2, 0x420, v1
	v_lshl_add_u32 v2, v0, 2, v2
	v_add_u32_e32 v189, s32, v2
	v_mul_u32_u24_e32 v2, 0x1000, v0
	v_lshl_add_u32 v183, v1, 4, v2
	v_add_u32_e32 v184, 0x8000, v183
	v_add_u32_e32 v185, 0x10000, v183
	v_add_u32_e32 v186, 0x18000, v183
	s_mov_b32 s81, s78
	s_mov_b32 s79, s78
	s_lshr_b32 s86, s79, 6
	s_and_b32 s87, s79, 0x3f
	s_mul_i32 s88, s86, 0x80000
	s_lshl_b32 s87, s87, 7
	s_add_u32 s88, s88, s87
	s_add_u32 s82, s8, s88
	s_addc_u32 s83, s9, 0
	global_load_dwordx4 v[4:7], v36, s[82:83]
	global_load_dwordx4 v[8:11], v37, s[82:83]
	global_load_dwordx4 v[12:15], v72, s[82:83]
	global_load_dwordx4 v[16:19], v73, s[82:83]
	global_load_dwordx4 v[20:23], v74, s[82:83]
	global_load_dwordx4 v[24:27], v75, s[82:83]
	global_load_dwordx4 v[28:31], v76, s[82:83]
	global_load_dwordx4 v[32:35], v182, s[82:83]
	s_add_u32 s79, s79, 0x300
	s_cmp_lt_u32 s79, 0x800
	s_cbranch_scc0 .Ltr_p1_t1wo
	s_lshr_b32 s86, s79, 6
	s_and_b32 s87, s79, 0x3f
	s_mul_i32 s88, s86, 0x80000
	s_lshl_b32 s87, s87, 7
	s_add_u32 s88, s88, s87
	s_add_u32 s82, s8, s88
	s_addc_u32 s83, s9, 0
	global_load_dwordx4 v[40:43], v36, s[82:83]
	global_load_dwordx4 v[44:47], v37, s[82:83]
	global_load_dwordx4 v[48:51], v72, s[82:83]
	global_load_dwordx4 v[52:55], v73, s[82:83]
	global_load_dwordx4 v[56:59], v74, s[82:83]
	global_load_dwordx4 v[60:63], v75, s[82:83]
	global_load_dwordx4 v[64:67], v76, s[82:83]
	global_load_dwordx4 v[68:71], v182, s[82:83]

; #define LAS __attribute__((address_space(3)))
; __device__ __forceinline__ unsigned cvtpk(float lo, float hi) { f32x2_t v = {lo, hi}; bf16x2_t b = __builtin_convertvector(v, bf16x2_t); return __builtin_bit_cast(unsigned, b); }
; template <int MODE>
; __device__ __forceinline__ void transpose_item(const float* W, int N, bf16_t* WT, int ldt, int coff, LAS float* scr, int item, int lane, const float* g) {
;     const int nblk = N / 32, kb = item / nblk, nb = item % nblk, k0 = 64 * kb, n0 = 32 * nb;
; #pragma unroll 8
;     for (int i = 0; i < 32; ++i) { const int kk = 2 * i + (lane >> 5); float v = W[(size_t)(k0 + kk) * N + n0 + (lane & 31)]; if (MODE >= 1) v *= g[k0 + kk]; scr[kk * 33 + (lane & 31)] = v; }
;     asm volatile("s_waitcnt lgkmcnt(0)" ::: "memory");
;     const int c = lane & 7;
; #pragma unroll
;     for (int j = 0; j < 4; ++j) {
;         const int n = (lane >> 3) + 8 * j; const LAS float* s = scr + (8 * c) * 33 + n;
;         u32x4 o; o.x = cvtpk(s[0 * 33], s[1 * 33]); o.y = cvtpk(s[2 * 33], s[3 * 33]); o.z = cvtpk(s[4 * 33], s[5 * 33]); o.w = cvtpk(s[6 * 33], s[7 * 33]);
;         int dr = n0 + n;
;         if (MODE == 1) { dr = (dr < DFF) ? 256 * (dr >> 7) + (dr & 127) : 256 * ((dr - DFF) >> 7) + 128 + ((dr - DFF) & 127); }
;         if (MODE == 2) {
;             if (dr >= 6144) { const int t = dr - 6144, ch = t & 2047; dr = 6144 + 256 * (ch >> 7) + ((t >> 11) << 7) + (ch & 127); }
;             else if (dr >= 4096) { const int t = dr - 4096, ch = t & 1023; dr = 4096 + 256 * (ch >> 7) + ((t >> 10) << 7) + (ch & 127); }
;         }
;         *(u32x4*)(WT + (size_t)dr * ldt + coff + k0 + 8 * c) = o;
;     }
;     asm volatile("s_waitcnt lgkmcnt(0)" ::: "memory");
; }
.Ltr_st0_t1wo:
	s_cmp_lt_u32 s79, 0x800
	s_cbranch_scc0 .Ltr_nl0_t1wo
	s_lshr_b32 s86, s79, 6
	s_and_b32 s87, s79, 0x3f
	s_mul_i32 s88, s86, 0x80000
	s_lshl_b32 s87, s87, 7
	s_add_u32 s88, s88, s87
	s_add_u32 s82, s8, s88
	s_addc_u32 s83, s9, 0
	global_load_dwordx4 v[96:99], v36, s[82:83]
	global_load_dwordx4 v[100:103], v37, s[82:83]
	global_load_dwordx4 v[104:107], v72, s[82:83]
	global_load_dwordx4 v[108:111], v73, s[82:83]
	global_load_dwordx4 v[112:115], v74, s[82:83]
	global_load_dwordx4 v[116:119], v75, s[82:83]
	global_load_dwordx4 v[120:123], v76, s[82:83]
	global_load_dwordx4 v[124:127], v182, s[82:83]
	s_waitcnt vmcnt(16)
	s_branch .Ltr_pr0_t1wo
.Ltr_nl0_t1wo:
	s_sub_u32 s86, s79, 0x300
	s_cmp_lt_u32 s86, 0x800
	s_cbranch_scc0 .Ltr_w00_t1wo
	s_waitcnt vmcnt(8)
	s_branch .Ltr_pr0_t1wo

; #define LAS __attribute__((address_space(3)))
; __device__ __forceinline__ unsigned cvtpk(float lo, float hi) { f32x2_t v = {lo, hi}; bf16x2_t b = __builtin_convertvector(v, bf16x2_t); return __builtin_bit_cast(unsigned, b); }
; template <int MODE>
; __device__ __forceinline__ void transpose_item(const float* W, int N, bf16_t* WT, int ldt, int coff, LAS float* scr, int item, int lane, const float* g) {
;     const int nblk = N / 32, kb = item / nblk, nb = item % nblk, k0 = 64 * kb, n0 = 32 * nb;
; #pragma unroll 8
;     for (int i = 0; i < 32; ++i) { const int kk = 2 * i + (lane >> 5); float v = W[(size_t)(k0 + kk) * N + n0 + (lane & 31)]; if (MODE >= 1) v *= g[k0 + kk]; scr[kk * 33 + (lane & 31)] = v; }
;     asm volatile("s_waitcnt lgkmcnt(0)" ::: "memory");
;     const int c = lane & 7;
; #pragma unroll
;     for (int j = 0; j < 4; ++j) {
;         const int n = (lane >> 3) + 8 * j; const LAS float* s = scr + (8 * c) * 33 + n;
;         u32x4 o; o.x = cvtpk(s[0 * 33], s[1 * 33]); o.y = cvtpk(s[2 * 33], s[3 * 33]); o.z = cvtpk(s[4 * 33], s[5 * 33]); o.w = cvtpk(s[6 * 33], s[7 * 33]);
;         int dr = n0 + n;
;         if (MODE == 1) { dr = (dr < DFF) ? 256 * (dr >> 7) + (dr & 127) : 256 * ((dr - DFF) >> 7) + 128 + ((dr - DFF) & 127); }
;         if (MODE == 2) {
;             if (dr >= 6144) { const int t = dr - 6144, ch = t & 2047; dr = 6144 + 256 * (ch >> 7) + ((t >> 11) << 7) + (ch & 127); }
;             else if (dr >= 4096) { const int t = dr - 4096, ch = t & 1023; dr = 4096 + 256 * (ch >> 7) + ((t >> 10) << 7) + (ch & 127); }
;         }
;         *(u32x4*)(WT + (size_t)dr * ldt + coff + k0 + 8 * c) = o;
;     }
;     asm volatile("s_waitcnt lgkmcnt(0)" ::: "memory");
; }
.Ltr_pr0_t1wo:
	s_add_u32 s79, s79, 0x300
	s_lshr_b32 s86, s81, 6
	s_and_b32 s87, s81, 0x3f
	s_mul_i32 s88, s87, 0x20000
	s_lshl_b32 s86, s86, 7
	s_add_u32 s88, s88, s86
	s_add_u32 s84, s72, s88
	s_addc_u32 s85, s73, 0
	ds_write_b32 v188, v4 offset:0
	ds_write_b32 v188, v5 offset:4
	ds_write_b32 v188, v6 offset:8
	ds_write_b32 v188, v7 offset:12
	ds_write_b32 v188, v8 offset:1056
	ds_write_b32 v188, v9 offset:1060
	ds_write_b32 v188, v10 offset:1064
	ds_write_b32 v188, v11 offset:1068
	ds_write_b32 v188, v12 offset:2112
	ds_write_b32 v188, v13 offset:2116
	ds_write_b32 v188, v14 offset:2120
	ds_write_b32 v188, v15 offset:2124
	ds_write_b32 v188, v16 offset:3168
	ds_write_b32 v188, v17 offset:3172
	ds_write_b32 v188, v18 offset:3176
	ds_write_b32 v188, v19 offset:3180
	ds_write_b32 v188, v20 offset:4224
	ds_write_b32 v188, v21 offset:4228
	ds_write_b32 v188, v22 offset:4232
	ds_write_b32 v188, v23 offset:4236
	ds_write_b32 v188, v24 offset:5280
	ds_write_b32 v188, v25 offset:5284
	ds_write_b32 v188, v26 offset:5288
	ds_write_b32 v188, v27 offset:5292
	ds_write_b32 v188, v28 offset:6336
	ds_write_b32 v188, v29 offset:6340
	ds_write_b32 v188, v30 offset:6344
	ds_write_b32 v188, v31 offset:6348
	ds_write_b32 v188, v32 offset:7392
	ds_write_b32 v188, v33 offset:7396
	ds_write_b32 v188, v34 offset:7400
	ds_write_b32 v188, v35 offset:7404
	s_waitcnt lgkmcnt(0)
	ds_read2_b32 v[128:129], v189 offset0:0 offset1:8
	ds_read2_b32 v[132:133], v189 offset0:33 offset1:41
	ds_read2_b32 v[136:137], v189 offset0:66 offset1:74
	ds_read2_b32 v[140:141], v189 offset0:99 offset1:107
	ds_read2_b32 v[144:145], v189 offset0:132 offset1:140
	ds_read2_b32 v[148:149], v189 offset0:165 offset1:173
	ds_read2_b32 v[152:153], v189 offset0:198 offset1:206
	ds_read2_b32 v[156:157], v189 offset0:231 offset1:239
	ds_read2_b32 v[130:131], v189 offset0:16 offset1:24
	ds_read2_b32 v[134:135], v189 offset0:49 offset1:57
	ds_read2_b32 v[138:139], v189 offset0:82 offset1:90
	ds_read2_b32 v[142:143], v189 offset0:115 offset1:123
	ds_read2_b32 v[146:147], v189 offset0:148 offset1:156
	ds_read2_b32 v[150:151], v189 offset0:181 offset1:189
	ds_read2_b32 v[154:155], v189 offset0:214 offset1:222
	ds_read2_b32 v[158:159], v189 offset0:247 offset1:255
	s_waitcnt lgkmcnt(0)
	v_cvt_pk_bf16_f32 v204, v128, v132
	v_cvt_pk_bf16_f32 v205, v136, v140
	v_cvt_pk_bf16_f32 v206, v144, v148
	v_cvt_pk_bf16_f32 v207, v152, v156
	global_store_dwordx4 v183, v[204:207], s[84:85]
	v_cvt_pk_bf16_f32 v208, v129, v133
	v_cvt_pk_bf16_f32 v209, v137, v141
	v_cvt_pk_bf16_f32 v210, v145, v149
	v_cvt_pk_bf16_f32 v211, v153, v157
	global_store_dwordx4 v184, v[208:211], s[84:85]
	v_cvt_pk_bf16_f32 v212, v130, v134
	v_cvt_pk_bf16_f32 v213, v138, v142
	v_cvt_pk_bf16_f32 v214, v146, v150
	v_cvt_pk_bf16_f32 v215, v154, v158
	global_store_dwordx4 v185, v[212:215], s[84:85]
	v_cvt_pk_bf16_f32 v216, v131, v135
	v_cvt_pk_bf16_f32 v217, v139, v143
	v_cvt_pk_bf16_f32 v218, v147, v151
	v_cvt_pk_bf16_f32 v219, v155, v159
	global_store_dwordx4 v186, v[216:219], s[84:85]
	s_add_u32 s81, s81, 0x300
	s_cmp_lt_u32 s81, 0x800
	s_cbranch_scc0 .Ltr_done_t1wo
.Ltr_st1_t1wo:
	s_cmp_lt_u32 s79, 0x800
	s_cbranch_scc0 .Ltr_nl1_t1wo
	s_lshr_b32 s86, s79, 6
	s_and_b32 s87, s79, 0x3f
	s_mul_i32 s88, s86, 0x80000
	s_lshl_b32 s87, s87, 7
	s_add_u32 s88, s88, s87
	s_add_u32 s82, s8, s88
	s_addc_u32 s83, s9, 0
	global_load_dwordx4 v[4:7], v36, s[82:83]
	global_load_dwordx4 v[8:11], v37, s[82:83]
	global_load_dwordx4 v[12:15], v72, s[82:83]
	global_load_dwordx4 v[16:19], v73, s[82:83]
	global_load_dwordx4 v[20:23], v74, s[82:83]
	global_load_dwordx4 v[24:27], v75, s[82:83]
	global_load_dwordx4 v[28:31], v76, s[82:83]
	global_load_dwordx4 v[32:35], v182, s[82:83]
	s_waitcnt vmcnt(16)
	s_branch .Ltr_pr1_t1wo

; #define LAS __attribute__((address_space(3)))
; __device__ __forceinline__ unsigned cvtpk(float lo, float hi) { f32x2_t v = {lo, hi}; bf16x2_t b = __builtin_convertvector(v, bf16x2_t); return __builtin_bit_cast(unsigned, b); }
; template <int MODE>
; __device__ __forceinline__ void transpose_item(const float* W, int N, bf16_t* WT, int ldt, int coff, LAS float* scr, int item, int lane, const float* g) {
;     const int nblk = N / 32, kb = item / nblk, nb = item % nblk, k0 = 64 * kb, n0 = 32 * nb;
; #pragma unroll 8
;     for (int i = 0; i < 32; ++i) { const int kk = 2 * i + (lane >> 5); float v = W[(size_t)(k0 + kk) * N + n0 + (lane & 31)]; if (MODE >= 1) v *= g[k0 + kk]; scr[kk * 33 + (lane & 31)] = v; }
;     asm volatile("s_waitcnt lgkmcnt(0)" ::: "memory");
;     const int c = lane & 7;
; #pragma unroll
;     for (int j = 0; j < 4; ++j) {
;         const int n = (lane >> 3) + 8 * j; const LAS float* s = scr + (8 * c) * 33 + n;
;         u32x4 o; o.x = cvtpk(s[0 * 33], s[1 * 33]); o.y = cvtpk(s[2 * 33], s[3 * 33]); o.z = cvtpk(s[4 * 33], s[5 * 33]); o.w = cvtpk(s[6 * 33], s[7 * 33]);
;         int dr = n0 + n;
;         if (MODE == 1) { dr = (dr < DFF) ? 256 * (dr >> 7) + (dr & 127) : 256 * ((dr - DFF) >> 7) + 128 + ((dr - DFF) & 127); }
;         if (MODE == 2) {
;             if (dr >= 6144) { const int t = dr - 6144, ch = t & 2047; dr = 6144 + 256 * (ch >> 7) + ((t >> 11) << 7) + (ch & 127); }
;             else if (dr >= 4096) { const int t = dr - 4096, ch = t & 1023; dr = 4096 + 256 * (ch >> 7) + ((t >> 10) << 7) + (ch & 127); }
;         }
;         *(u32x4*)(WT + (size_t)dr * ldt + coff + k0 + 8 * c) = o;
;     }
;     asm volatile("s_waitcnt lgkmcnt(0)" ::: "memory");
; }
.Ltr_pr1_t1wo:
	s_add_u32 s79, s79, 0x300
	s_lshr_b32 s86, s81, 6
	s_and_b32 s87, s81, 0x3f
	s_mul_i32 s88, s87, 0x20000
	s_lshl_b32 s86, s86, 7
	s_add_u32 s88, s88, s86
	s_add_u32 s84, s72, s88
	s_addc_u32 s85, s73, 0
	ds_write_b32 v188, v40 offset:0
	ds_write_b32 v188, v41 offset:4
	ds_write_b32 v188, v42 offset:8
	ds_write_b32 v188, v43 offset:12
	ds_write_b32 v188, v44 offset:1056
	ds_write_b32 v188, v45 offset:1060
	ds_write_b32 v188, v46 offset:1064
	ds_write_b32 v188, v47 offset:1068
	ds_write_b32 v188, v48 offset:2112
	ds_write_b32 v188, v49 offset:2116
	ds_write_b32 v188, v50 offset:2120
	ds_write_b32 v188, v51 offset:2124
	ds_write_b32 v188, v52 offset:3168
	ds_write_b32 v188, v53 offset:3172
	ds_write_b32 v188, v54 offset:3176
	ds_write_b32 v188, v55 offset:3180
	ds_write_b32 v188, v56 offset:4224
	ds_write_b32 v188, v57 offset:4228
	ds_write_b32 v188, v58 offset:4232
	ds_write_b32 v188, v59 offset:4236
	ds_write_b32 v188, v60 offset:5280
	ds_write_b32 v188, v61 offset:5284
	ds_write_b32 v188, v62 offset:5288
	ds_write_b32 v188, v63 offset:5292
	ds_write_b32 v188, v64 offset:6336
	ds_write_b32 v188, v65 offset:6340
	ds_write_b32 v188, v66 offset:6344
	ds_write_b32 v188, v67 offset:6348
	ds_write_b32 v188, v68 offset:7392
	ds_write_b32 v188, v69 offset:7396
	ds_write_b32 v188, v70 offset:7400
	ds_write_b32 v188, v71 offset:7404
	s_waitcnt lgkmcnt(0)
	ds_read2_b32 v[128:129], v189 offset0:0 offset1:8
	ds_read2_b32 v[132:133], v189 offset0:33 offset1:41
	ds_read2_b32 v[136:137], v189 offset0:66 offset1:74
	ds_read2_b32 v[140:141], v189 offset0:99 offset1:107
	ds_read2_b32 v[144:145], v189 offset0:132 offset1:140
	ds_read2_b32 v[148:149], v189 offset0:165 offset1:173
	ds_read2_b32 v[152:153], v189 offset0:198 offset1:206
	ds_read2_b32 v[156:157], v189 offset0:231 offset1:239
	ds_read2_b32 v[130:131], v189 offset0:16 offset1:24
	ds_read2_b32 v[134:135], v189 offset0:49 offset1:57
	ds_read2_b32 v[138:139], v189 offset0:82 offset1:90
	ds_read2_b32 v[142:143], v189 offset0:115 offset1:123
	ds_read2_b32 v[146:147], v189 offset0:148 offset1:156
	ds_read2_b32 v[150:151], v189 offset0:181 offset1:189
	ds_read2_b32 v[154:155], v189 offset0:214 offset1:222
	ds_read2_b32 v[158:159], v189 offset0:247 offset1:255
	s_waitcnt lgkmcnt(0)
	v_cvt_pk_bf16_f32 v204, v128, v132
	v_cvt_pk_bf16_f32 v205, v136, v140
	v_cvt_pk_bf16_f32 v206, v144, v148
	v_cvt_pk_bf16_f32 v207, v152, v156
	global_store_dwordx4 v183, v[204:207], s[84:85]
	v_cvt_pk_bf16_f32 v208, v129, v133
	v_cvt_pk_bf16_f32 v209, v137, v141
	v_cvt_pk_bf16_f32 v210, v145, v149
	v_cvt_pk_bf16_f32 v211, v153, v157
	global_store_dwordx4 v184, v[208:211], s[84:85]
	v_cvt_pk_bf16_f32 v212, v130, v134
	v_cvt_pk_bf16_f32 v213, v138, v142
	v_cvt_pk_bf16_f32 v214, v146, v150
	v_cvt_pk_bf16_f32 v215, v154, v158
	global_store_dwordx4 v185, v[212:215], s[84:85]
	v_cvt_pk_bf16_f32 v216, v131, v135
	v_cvt_pk_bf16_f32 v217, v139, v143
	v_cvt_pk_bf16_f32 v218, v147, v151
	v_cvt_pk_bf16_f32 v219, v155, v159
	global_store_dwordx4 v186, v[216:219], s[84:85]
	s_add_u32 s81, s81, 0x300
	s_cmp_lt_u32 s81, 0x800
	s_cbranch_scc0 .Ltr_done_t1wo
.Ltr_st2_t1wo:
	s_cmp_lt_u32 s79, 0x800
	s_cbranch_scc0 .Ltr_nl2_t1wo
	s_lshr_b32 s86, s79, 6
	s_and_b32 s87, s79, 0x3f
	s_mul_i32 s88, s86, 0x80000
	s_lshl_b32 s87, s87, 7
	s_add_u32 s88, s88, s87
	s_add_u32 s82, s8, s88
	s_addc_u32 s83, s9, 0
	global_load_dwordx4 v[40:43], v36, s[82:83]
	global_load_dwordx4 v[44:47], v37, s[82:83]
	global_load_dwordx4 v[48:51], v72, s[82:83]
	global_load_dwordx4 v[52:55], v73, s[82:83]
	global_load_dwordx4 v[56:59], v74, s[82:83]
	global_load_dwordx4 v[60:63], v75, s[82:83]
	global_load_dwordx4 v[64:67], v76, s[82:83]
	global_load_dwordx4 v[68:71], v182, s[82:83]
	s_waitcnt vmcnt(16)
	s_branch .Ltr_pr2_t1wo

; #define LAS __attribute__((address_space(3)))
; __device__ __forceinline__ unsigned cvtpk(float lo, float hi) { f32x2_t v = {lo, hi}; bf16x2_t b = __builtin_convertvector(v, bf16x2_t); return __builtin_bit_cast(unsigned, b); }
; template <int MODE>
; __device__ __forceinline__ void transpose_item(const float* W, int N, bf16_t* WT, int ldt, int coff, LAS float* scr, int item, int lane, const float* g) {
;     const int nblk = N / 32, kb = item / nblk, nb = item % nblk, k0 = 64 * kb, n0 = 32 * nb;
; #pragma unroll 8
;     for (int i = 0; i < 32; ++i) { const int kk = 2 * i + (lane >> 5); float v = W[(size_t)(k0 + kk) * N + n0 + (lane & 31)]; if (MODE >= 1) v *= g[k0 + kk]; scr[kk * 33 + (lane & 31)] = v; }
;     asm volatile("s_waitcnt lgkmcnt(0)" ::: "memory");
;     const int c = lane & 7;
; #pragma unroll
;     for (int j = 0; j < 4; ++j) {
;         const int n = (lane >> 3) + 8 * j; const LAS float* s = scr + (8 * c) * 33 + n;
;         u32x4 o; o.x = cvtpk(s[0 * 33], s[1 * 33]); o.y = cvtpk(s[2 * 33], s[3 * 33]); o.z = cvtpk(s[4 * 33], s[5 * 33]); o.w = cvtpk(s[6 * 33], s[7 * 33]);
;         int dr = n0 + n;
;         if (MODE == 1) { dr = (dr < DFF) ? 256 * (dr >> 7) + (dr & 127) : 256 * ((dr - DFF) >> 7) + 128 + ((dr - DFF) & 127); }
;         if (MODE == 2) {
;             if (dr >= 6144) { const int t = dr - 6144, ch = t & 2047; dr = 6144 + 256 * (ch >> 7) + ((t >> 11) << 7) + (ch & 127); }
;             else if (dr >= 4096) { const int t = dr - 4096, ch = t & 1023; dr = 4096 + 256 * (ch >> 7) + ((t >> 10) << 7) + (ch & 127); }
;         }
;         *(u32x4*)(WT + (size_t)dr * ldt + coff + k0 + 8 * c) = o;
;     }
;     asm volatile("s_waitcnt lgkmcnt(0)" ::: "memory");
; }
; __global__ void __launch_bounds__(512, 2) mk_fwd(Args a) {
;     ...
;             { const int bb = r / I_V; transpose_item<0>(a.in[I_CV] + (size_t)bb * PAST * 1024, 1024, VTC + (size_t)bb * 1024 * PAST, PAST, 0, scr, r % I_V, lane, nullptr); }
.Ltr_pr2_t1wo:
	s_add_u32 s79, s79, 0x300
	s_lshr_b32 s86, s81, 6
	s_and_b32 s87, s81, 0x3f
	s_mul_i32 s88, s87, 0x20000
	s_lshl_b32 s86, s86, 7
	s_add_u32 s88, s88, s86
	s_add_u32 s84, s72, s88
	s_addc_u32 s85, s73, 0
	ds_write_b32 v188, v96 offset:0
	ds_write_b32 v188, v97 offset:4
	ds_write_b32 v188, v98 offset:8
	ds_write_b32 v188, v99 offset:12
	ds_write_b32 v188, v100 offset:1056
	ds_write_b32 v188, v101 offset:1060
	ds_write_b32 v188, v102 offset:1064
	ds_write_b32 v188, v103 offset:1068
	ds_write_b32 v188, v104 offset:2112
	ds_write_b32 v188, v105 offset:2116
	ds_write_b32 v188, v106 offset:2120
	ds_write_b32 v188, v107 offset:2124
	ds_write_b32 v188, v108 offset:3168
	ds_write_b32 v188, v109 offset:3172
	ds_write_b32 v188, v110 offset:3176
	ds_write_b32 v188, v111 offset:3180
	ds_write_b32 v188, v112 offset:4224
	ds_write_b32 v188, v113 offset:4228
	ds_write_b32 v188, v114 offset:4232
	ds_write_b32 v188, v115 offset:4236
	ds_write_b32 v188, v116 offset:5280
	ds_write_b32 v188, v117 offset:5284
	ds_write_b32 v188, v118 offset:5288
	ds_write_b32 v188, v119 offset:5292
	ds_write_b32 v188, v120 offset:6336
	ds_write_b32 v188, v121 offset:6340
	ds_write_b32 v188, v122 offset:6344
	ds_write_b32 v188, v123 offset:6348
	ds_write_b32 v188, v124 offset:7392
	ds_write_b32 v188, v125 offset:7396
	ds_write_b32 v188, v126 offset:7400
	ds_write_b32 v188, v127 offset:7404
	s_waitcnt lgkmcnt(0)
	ds_read2_b32 v[128:129], v189 offset0:0 offset1:8
	ds_read2_b32 v[132:133], v189 offset0:33 offset1:41
	ds_read2_b32 v[136:137], v189 offset0:66 offset1:74
	ds_read2_b32 v[140:141], v189 offset0:99 offset1:107
	ds_read2_b32 v[144:145], v189 offset0:132 offset1:140
	ds_read2_b32 v[148:149], v189 offset0:165 offset1:173
	ds_read2_b32 v[152:153], v189 offset0:198 offset1:206
	ds_read2_b32 v[156:157], v189 offset0:231 offset1:239
	ds_read2_b32 v[130:131], v189 offset0:16 offset1:24
	ds_read2_b32 v[134:135], v189 offset0:49 offset1:57
	ds_read2_b32 v[138:139], v189 offset0:82 offset1:90
	ds_read2_b32 v[142:143], v189 offset0:115 offset1:123
	ds_read2_b32 v[146:147], v189 offset0:148 offset1:156
	ds_read2_b32 v[150:151], v189 offset0:181 offset1:189
	ds_read2_b32 v[154:155], v189 offset0:214 offset1:222
	ds_read2_b32 v[158:159], v189 offset0:247 offset1:255
	s_waitcnt lgkmcnt(0)
	v_cvt_pk_bf16_f32 v204, v128, v132
	v_cvt_pk_bf16_f32 v205, v136, v140
	v_cvt_pk_bf16_f32 v206, v144, v148
	v_cvt_pk_bf16_f32 v207, v152, v156
	global_store_dwordx4 v183, v[204:207], s[84:85]
	v_cvt_pk_bf16_f32 v208, v129, v133
	v_cvt_pk_bf16_f32 v209, v137, v141
	v_cvt_pk_bf16_f32 v210, v145, v149
	v_cvt_pk_bf16_f32 v211, v153, v157
	global_store_dwordx4 v184, v[208:211], s[84:85]
	v_cvt_pk_bf16_f32 v212, v130, v134
	v_cvt_pk_bf16_f32 v213, v138, v142
	v_cvt_pk_bf16_f32 v214, v146, v150
	v_cvt_pk_bf16_f32 v215, v154, v158
	global_store_dwordx4 v185, v[212:215], s[84:85]
	v_cvt_pk_bf16_f32 v216, v131, v135
	v_cvt_pk_bf16_f32 v217, v139, v143
	v_cvt_pk_bf16_f32 v218, v147, v151
	v_cvt_pk_bf16_f32 v219, v155, v159
	global_store_dwordx4 v186, v[216:219], s[84:85]
	s_add_u32 s81, s81, 0x300
	s_cmp_lt_u32 s81, 0x800
	s_cbranch_scc0 .Ltr_done_t1wo
	s_branch .Ltr_st0_t1wo
.Ltr_done_t1wo:
	s_cmp_lt_u32 s67, 0x2000
	s_cbranch_scc0 .Ltr_done_t1vt
	v_lshrrev_b32_e32 v0, 3, v220
	v_and_b32_e32 v1, 7, v220
	v_mul_u32_u24_e32 v2, 0x1000, v0
	v_lshl_add_u32 v36, v1, 4, v2
	v_add_u32_e32 v37, 0x8000, v36
	v_add_u32_e32 v72, 0x10000, v36
	v_add_u32_e32 v73, 0x18000, v36
	v_add_u32_e32 v74, 0x20000, v36
	v_add_u32_e32 v75, 0x28000, v36
	v_add_u32_e32 v76, 0x30000, v36
	v_add_u32_e32 v182, 0x38000, v36
	v_mul_u32_u24_e32 v2, 0x84, v0
	v_lshl_add_u32 v2, v1, 4, v2
	v_add_u32_e32 v188, s32, v2
	v_mul_u32_u24_e32 v2, 0x420, v1
	v_lshl_add_u32 v2, v0, 2, v2
	v_add_u32_e32 v189, s32, v2
	v_mul_u32_u24_e32 v2, 0x800, v0
	v_lshl_add_u32 v183, v1, 4, v2
	v_add_u32_e32 v184, 0x4000, v183
	v_add_u32_e32 v185, 0x8000, v183
	v_add_u32_e32 v186, 0xc000, v183
	s_mov_b32 s81, s67
	s_mov_b32 s79, s67
	s_lshr_b32 s89, s79, 9
	s_and_b32 s88, s79, 0x1ff
	s_lshr_b32 s86, s88, 5
	s_and_b32 s87, s88, 0x1f
	s_mul_i32 s88, s86, 0x40000
	s_lshl_b32 s87, s87, 7
	s_add_u32 s88, s88, s87
	s_mul_i32 s87, s89, 0x400000
	s_add_u32 s88, s88, s87
	s_add_u32 s82, s18, s88
	s_addc_u32 s83, s19, 0
	global_load_dwordx4 v[4:7], v36, s[82:83]
	global_load_dwordx4 v[8:11], v37, s[82:83]
	global_load_dwordx4 v[12:15], v72, s[82:83]
	global_load_dwordx4 v[16:19], v73, s[82:83]
	global_load_dwordx4 v[20:23], v74, s[82:83]
	global_load_dwordx4 v[24:27], v75, s[82:83]
	global_load_dwordx4 v[28:31], v76, s[82:83]
	global_load_dwordx4 v[32:35], v182, s[82:83]
	s_add_u32 s79, s79, 0x300
	s_cmp_lt_u32 s79, 0x2000
	s_cbranch_scc0 .Ltr_p1_t1vt
	s_lshr_b32 s89, s79, 9
	s_and_b32 s88, s79, 0x1ff
	s_lshr_b32 s86, s88, 5
	s_and_b32 s87, s88, 0x1f
	s_mul_i32 s88, s86, 0x40000
	s_lshl_b32 s87, s87, 7
	s_add_u32 s88, s88, s87
	s_mul_i32 s87, s89, 0x400000
	s_add_u32 s88, s88, s87
	s_add_u32 s82, s18, s88
	s_addc_u32 s83, s19, 0
	global_load_dwordx4 v[40:43], v36, s[82:83]
	global_load_dwordx4 v[44:47], v37, s[82:83]
	global_load_dwordx4 v[48:51], v72, s[82:83]
	global_load_dwordx4 v[52:55], v73, s[82:83]
	global_load_dwordx4 v[56:59], v74, s[82:83]
	global_load_dwordx4 v[60:63], v75, s[82:83]
	global_load_dwordx4 v[64:67], v76, s[82:83]
	global_load_dwordx4 v[68:71], v182, s[82:83]

; #define LAS __attribute__((address_space(3)))
; __device__ __forceinline__ unsigned cvtpk(float lo, float hi) { f32x2_t v = {lo, hi}; bf16x2_t b = __builtin_convertvector(v, bf16x2_t); return __builtin_bit_cast(unsigned, b); }
; template <int MODE>
; __device__ __forceinline__ void transpose_item(const float* W, int N, bf16_t* WT, int ldt, int coff, LAS float* scr, int item, int lane, const float* g) {
;     const int nblk = N / 32, kb = item / nblk, nb = item % nblk, k0 = 64 * kb, n0 = 32 * nb;
; #pragma unroll 8
;     for (int i = 0; i < 32; ++i) { const int kk = 2 * i + (lane >> 5); float v = W[(size_t)(k0 + kk) * N + n0 + (lane & 31)]; if (MODE >= 1) v *= g[k0 + kk]; scr[kk * 33 + (lane & 31)] = v; }
;     asm volatile("s_waitcnt lgkmcnt(0)" ::: "memory");
;     const int c = lane & 7;
; #pragma unroll
;     for (int j = 0; j < 4; ++j) {
;         const int n = (lane >> 3) + 8 * j; const LAS float* s = scr + (8 * c) * 33 + n;
;         u32x4 o; o.x = cvtpk(s[0 * 33], s[1 * 33]); o.y = cvtpk(s[2 * 33], s[3 * 33]); o.z = cvtpk(s[4 * 33], s[5 * 33]); o.w = cvtpk(s[6 * 33], s[7 * 33]);
;         int dr = n0 + n;
;         if (MODE == 1) { dr = (dr < DFF) ? 256 * (dr >> 7) + (dr & 127) : 256 * ((dr - DFF) >> 7) + 128 + ((dr - DFF) & 127); }
;         if (MODE == 2) {
;             if (dr >= 6144) { const int t = dr - 6144, ch = t & 2047; dr = 6144 + 256 * (ch >> 7) + ((t >> 11) << 7) + (ch & 127); }
;             else if (dr >= 4096) { const int t = dr - 4096, ch = t & 1023; dr = 4096 + 256 * (ch >> 7) + ((t >> 10) << 7) + (ch & 127); }
;         }
;         *(u32x4*)(WT + (size_t)dr * ldt + coff + k0 + 8 * c) = o;
;     }
;     asm volatile("s_waitcnt lgkmcnt(0)" ::: "memory");
; }
.Ltr_st0_t1vt:
	s_cmp_lt_u32 s79, 0x2000
	s_cbranch_scc0 .Ltr_nl0_t1vt
	s_lshr_b32 s89, s79, 9
	s_and_b32 s88, s79, 0x1ff
	s_lshr_b32 s86, s88, 5
	s_and_b32 s87, s88, 0x1f
	s_mul_i32 s88, s86, 0x40000
	s_lshl_b32 s87, s87, 7
	s_add_u32 s88, s88, s87
	s_mul_i32 s87, s89, 0x400000
	s_add_u32 s88, s88, s87
	s_add_u32 s82, s18, s88
	s_addc_u32 s83, s19, 0
	global_load_dwordx4 v[96:99], v36, s[82:83]
	global_load_dwordx4 v[100:103], v37, s[82:83]
	global_load_dwordx4 v[104:107], v72, s[82:83]
	global_load_dwordx4 v[108:111], v73, s[82:83]
	global_load_dwordx4 v[112:115], v74, s[82:83]
	global_load_dwordx4 v[116:119], v75, s[82:83]
	global_load_dwordx4 v[120:123], v76, s[82:83]
	global_load_dwordx4 v[124:127], v182, s[82:83]
	s_waitcnt vmcnt(16)
	s_branch .Ltr_pr0_t1vt
.Ltr_nl0_t1vt:
	s_sub_u32 s86, s79, 0x300
	s_cmp_lt_u32 s86, 0x2000
	s_cbranch_scc0 .Ltr_w00_t1vt
	s_waitcnt vmcnt(8)
	s_branch .Ltr_pr0_t1vt

; #define LAS __attribute__((address_space(3)))
; __device__ __forceinline__ unsigned cvtpk(float lo, float hi) { f32x2_t v = {lo, hi}; bf16x2_t b = __builtin_convertvector(v, bf16x2_t); return __builtin_bit_cast(unsigned, b); }
; template <int MODE>
; __device__ __forceinline__ void transpose_item(const float* W, int N, bf16_t* WT, int ldt, int coff, LAS float* scr, int item, int lane, const float* g) {
;     const int nblk = N / 32, kb = item / nblk, nb = item % nblk, k0 = 64 * kb, n0 = 32 * nb;
; #pragma unroll 8
;     for (int i = 0; i < 32; ++i) { const int kk = 2 * i + (lane >> 5); float v = W[(size_t)(k0 + kk) * N + n0 + (lane & 31)]; if (MODE >= 1) v *= g[k0 + kk]; scr[kk * 33 + (lane & 31)] = v; }
;     asm volatile("s_waitcnt lgkmcnt(0)" ::: "memory");
;     const int c = lane & 7;
; #pragma unroll
;     for (int j = 0; j < 4; ++j) {
;         const int n = (lane >> 3) + 8 * j; const LAS float* s = scr + (8 * c) * 33 + n;
;         u32x4 o; o.x = cvtpk(s[0 * 33], s[1 * 33]); o.y = cvtpk(s[2 * 33], s[3 * 33]); o.z = cvtpk(s[4 * 33], s[5 * 33]); o.w = cvtpk(s[6 * 33], s[7 * 33]);
;         int dr = n0 + n;
;         if (MODE == 1) { dr = (dr < DFF) ? 256 * (dr >> 7) + (dr & 127) : 256 * ((dr - DFF) >> 7) + 128 + ((dr - DFF) & 127); }
;         if (MODE == 2) {
;             if (dr >= 6144) { const int t = dr - 6144, ch = t & 2047; dr = 6144 + 256 * (ch >> 7) + ((t >> 11) << 7) + (ch & 127); }
;             else if (dr >= 4096) { const int t = dr - 4096, ch = t & 1023; dr = 4096 + 256 * (ch >> 7) + ((t >> 10) << 7) + (ch & 127); }
;         }
;         *(u32x4*)(WT + (size_t)dr * ldt + coff + k0 + 8 * c) = o;
;     }
;     asm volatile("s_waitcnt lgkmcnt(0)" ::: "memory");
; }
.Ltr_pr0_t1vt:
	s_add_u32 s79, s79, 0x300
	s_lshr_b32 s89, s81, 9
	s_and_b32 s88, s81, 0x1ff
	s_lshr_b32 s86, s88, 5
	s_and_b32 s87, s88, 0x1f
	s_mul_i32 s88, s87, 0x10000
	s_lshl_b32 s86, s86, 7
	s_add_u32 s88, s88, s86
	s_mul_i32 s87, s89, 0x200000
	s_add_u32 s88, s88, s87
	s_add_u32 s84, s74, s88
	s_addc_u32 s85, s75, 0
	ds_write_b32 v188, v4 offset:0
	ds_write_b32 v188, v5 offset:4
	ds_write_b32 v188, v6 offset:8
	ds_write_b32 v188, v7 offset:12
	ds_write_b32 v188, v8 offset:1056
	ds_write_b32 v188, v9 offset:1060
	ds_write_b32 v188, v10 offset:1064
	ds_write_b32 v188, v11 offset:1068
	ds_write_b32 v188, v12 offset:2112
	ds_write_b32 v188, v13 offset:2116
	ds_write_b32 v188, v14 offset:2120
	ds_write_b32 v188, v15 offset:2124
	ds_write_b32 v188, v16 offset:3168
	ds_write_b32 v188, v17 offset:3172
	ds_write_b32 v188, v18 offset:3176
	ds_write_b32 v188, v19 offset:3180
	ds_write_b32 v188, v20 offset:4224
	ds_write_b32 v188, v21 offset:4228
	ds_write_b32 v188, v22 offset:4232
	ds_write_b32 v188, v23 offset:4236
	ds_write_b32 v188, v24 offset:5280
	ds_write_b32 v188, v25 offset:5284
	ds_write_b32 v188, v26 offset:5288
	ds_write_b32 v188, v27 offset:5292
	ds_write_b32 v188, v28 offset:6336
	ds_write_b32 v188, v29 offset:6340
	ds_write_b32 v188, v30 offset:6344
	ds_write_b32 v188, v31 offset:6348
	ds_write_b32 v188, v32 offset:7392
	ds_write_b32 v188, v33 offset:7396
	ds_write_b32 v188, v34 offset:7400
	ds_write_b32 v188, v35 offset:7404
	s_waitcnt lgkmcnt(0)
	ds_read2_b32 v[128:129], v189 offset0:0 offset1:8
	ds_read2_b32 v[132:133], v189 offset0:33 offset1:41
	ds_read2_b32 v[136:137], v189 offset0:66 offset1:74
	ds_read2_b32 v[140:141], v189 offset0:99 offset1:107
	ds_read2_b32 v[144:145], v189 offset0:132 offset1:140
	ds_read2_b32 v[148:149], v189 offset0:165 offset1:173
	ds_read2_b32 v[152:153], v189 offset0:198 offset1:206
	ds_read2_b32 v[156:157], v189 offset0:231 offset1:239
	ds_read2_b32 v[130:131], v189 offset0:16 offset1:24
	ds_read2_b32 v[134:135], v189 offset0:49 offset1:57
	ds_read2_b32 v[138:139], v189 offset0:82 offset1:90
	ds_read2_b32 v[142:143], v189 offset0:115 offset1:123
	ds_read2_b32 v[146:147], v189 offset0:148 offset1:156
	ds_read2_b32 v[150:151], v189 offset0:181 offset1:189
	ds_read2_b32 v[154:155], v189 offset0:214 offset1:222
	ds_read2_b32 v[158:159], v189 offset0:247 offset1:255
	s_waitcnt lgkmcnt(0)
	v_cvt_pk_bf16_f32 v204, v128, v132
	v_cvt_pk_bf16_f32 v205, v136, v140
	v_cvt_pk_bf16_f32 v206, v144, v148
	v_cvt_pk_bf16_f32 v207, v152, v156
	global_store_dwordx4 v183, v[204:207], s[84:85]
	v_cvt_pk_bf16_f32 v208, v129, v133
	v_cvt_pk_bf16_f32 v209, v137, v141
	v_cvt_pk_bf16_f32 v210, v145, v149
	v_cvt_pk_bf16_f32 v211, v153, v157
	global_store_dwordx4 v184, v[208:211], s[84:85]
	v_cvt_pk_bf16_f32 v212, v130, v134
	v_cvt_pk_bf16_f32 v213, v138, v142
	v_cvt_pk_bf16_f32 v214, v146, v150
	v_cvt_pk_bf16_f32 v215, v154, v158
	global_store_dwordx4 v185, v[212:215], s[84:85]
	v_cvt_pk_bf16_f32 v216, v131, v135
	v_cvt_pk_bf16_f32 v217, v139, v143
	v_cvt_pk_bf16_f32 v218, v147, v151
	v_cvt_pk_bf16_f32 v219, v155, v159
	global_store_dwordx4 v186, v[216:219], s[84:85]
	s_add_u32 s81, s81, 0x300
	s_cmp_lt_u32 s81, 0x2000
	s_cbranch_scc0 .Ltr_done_t1vt
.Ltr_st1_t1vt:
	s_cmp_lt_u32 s79, 0x2000
	s_cbranch_scc0 .Ltr_nl1_t1vt
	s_lshr_b32 s89, s79, 9
	s_and_b32 s88, s79, 0x1ff
	s_lshr_b32 s86, s88, 5
	s_and_b32 s87, s88, 0x1f
	s_mul_i32 s88, s86, 0x40000
	s_lshl_b32 s87, s87, 7
	s_add_u32 s88, s88, s87
	s_mul_i32 s87, s89, 0x400000
	s_add_u32 s88, s88, s87
	s_add_u32 s82, s18, s88
	s_addc_u32 s83, s19, 0
	global_load_dwordx4 v[4:7], v36, s[82:83]
	global_load_dwordx4 v[8:11], v37, s[82:83]
	global_load_dwordx4 v[12:15], v72, s[82:83]
	global_load_dwordx4 v[16:19], v73, s[82:83]
	global_load_dwordx4 v[20:23], v74, s[82:83]
	global_load_dwordx4 v[24:27], v75, s[82:83]
	global_load_dwordx4 v[28:31], v76, s[82:83]
	global_load_dwordx4 v[32:35], v182, s[82:83]
	s_waitcnt vmcnt(16)
	s_branch .Ltr_pr1_t1vt

; #define LAS __attribute__((address_space(3)))
; __device__ __forceinline__ unsigned cvtpk(float lo, float hi) { f32x2_t v = {lo, hi}; bf16x2_t b = __builtin_convertvector(v, bf16x2_t); return __builtin_bit_cast(unsigned, b); }
; template <int MODE>
; __device__ __forceinline__ void transpose_item(const float* W, int N, bf16_t* WT, int ldt, int coff, LAS float* scr, int item, int lane, const float* g) {
;     const int nblk = N / 32, kb = item / nblk, nb = item % nblk, k0 = 64 * kb, n0 = 32 * nb;
; #pragma unroll 8
;     for (int i = 0; i < 32; ++i) { const int kk = 2 * i + (lane >> 5); float v = W[(size_t)(k0 + kk) * N + n0 + (lane & 31)]; if (MODE >= 1) v *= g[k0 + kk]; scr[kk * 33 + (lane & 31)] = v; }
;     asm volatile("s_waitcnt lgkmcnt(0)" ::: "memory");
;     const int c = lane & 7;
; #pragma unroll
;     for (int j = 0; j < 4; ++j) {
;         const int n = (lane >> 3) + 8 * j; const LAS float* s = scr + (8 * c) * 33 + n;
;         u32x4 o; o.x = cvtpk(s[0 * 33], s[1 * 33]); o.y = cvtpk(s[2 * 33], s[3 * 33]); o.z = cvtpk(s[4 * 33], s[5 * 33]); o.w = cvtpk(s[6 * 33], s[7 * 33]);
;         int dr = n0 + n;
;         if (MODE == 1) { dr = (dr < DFF) ? 256 * (dr >> 7) + (dr & 127) : 256 * ((dr - DFF) >> 7) + 128 + ((dr - DFF) & 127); }
;         if (MODE == 2) {
;             if (dr >= 6144) { const int t = dr - 6144, ch = t & 2047; dr = 6144 + 256 * (ch >> 7) + ((t >> 11) << 7) + (ch & 127); }
;             else if (dr >= 4096) { const int t = dr - 4096, ch = t & 1023; dr = 4096 + 256 * (ch >> 7) + ((t >> 10) << 7) + (ch & 127); }
;         }
;         *(u32x4*)(WT + (size_t)dr * ldt + coff + k0 + 8 * c) = o;
;     }
;     asm volatile("s_waitcnt lgkmcnt(0)" ::: "memory");
; }
.Ltr_pr1_t1vt:
	s_add_u32 s79, s79, 0x300
	s_lshr_b32 s89, s81, 9
	s_and_b32 s88, s81, 0x1ff
	s_lshr_b32 s86, s88, 5
	s_and_b32 s87, s88, 0x1f
	s_mul_i32 s88, s87, 0x10000
	s_lshl_b32 s86, s86, 7
	s_add_u32 s88, s88, s86
	s_mul_i32 s87, s89, 0x200000
	s_add_u32 s88, s88, s87
	s_add_u32 s84, s74, s88
	s_addc_u32 s85, s75, 0
	ds_write_b32 v188, v40 offset:0
	ds_write_b32 v188, v41 offset:4
	ds_write_b32 v188, v42 offset:8
	ds_write_b32 v188, v43 offset:12
	ds_write_b32 v188, v44 offset:1056
	ds_write_b32 v188, v45 offset:1060
	ds_write_b32 v188, v46 offset:1064
	ds_write_b32 v188, v47 offset:1068
	ds_write_b32 v188, v48 offset:2112
	ds_write_b32 v188, v49 offset:2116
	ds_write_b32 v188, v50 offset:2120
	ds_write_b32 v188, v51 offset:2124
	ds_write_b32 v188, v52 offset:3168
	ds_write_b32 v188, v53 offset:3172
	ds_write_b32 v188, v54 offset:3176
	ds_write_b32 v188, v55 offset:3180
	ds_write_b32 v188, v56 offset:4224
	ds_write_b32 v188, v57 offset:4228
	ds_write_b32 v188, v58 offset:4232
	ds_write_b32 v188, v59 offset:4236
	ds_write_b32 v188, v60 offset:5280
	ds_write_b32 v188, v61 offset:5284
	ds_write_b32 v188, v62 offset:5288
	ds_write_b32 v188, v63 offset:5292
	ds_write_b32 v188, v64 offset:6336
	ds_write_b32 v188, v65 offset:6340
	ds_write_b32 v188, v66 offset:6344
	ds_write_b32 v188, v67 offset:6348
	ds_write_b32 v188, v68 offset:7392
	ds_write_b32 v188, v69 offset:7396
	ds_write_b32 v188, v70 offset:7400
	ds_write_b32 v188, v71 offset:7404
	s_waitcnt lgkmcnt(0)
	ds_read2_b32 v[128:129], v189 offset0:0 offset1:8
	ds_read2_b32 v[132:133], v189 offset0:33 offset1:41
	ds_read2_b32 v[136:137], v189 offset0:66 offset1:74
	ds_read2_b32 v[140:141], v189 offset0:99 offset1:107
	ds_read2_b32 v[144:145], v189 offset0:132 offset1:140
	ds_read2_b32 v[148:149], v189 offset0:165 offset1:173
	ds_read2_b32 v[152:153], v189 offset0:198 offset1:206
	ds_read2_b32 v[156:157], v189 offset0:231 offset1:239
	ds_read2_b32 v[130:131], v189 offset0:16 offset1:24
	ds_read2_b32 v[134:135], v189 offset0:49 offset1:57
	ds_read2_b32 v[138:139], v189 offset0:82 offset1:90
	ds_read2_b32 v[142:143], v189 offset0:115 offset1:123
	ds_read2_b32 v[146:147], v189 offset0:148 offset1:156
	ds_read2_b32 v[150:151], v189 offset0:181 offset1:189
	ds_read2_b32 v[154:155], v189 offset0:214 offset1:222
	ds_read2_b32 v[158:159], v189 offset0:247 offset1:255
	s_waitcnt lgkmcnt(0)
	v_cvt_pk_bf16_f32 v204, v128, v132
	v_cvt_pk_bf16_f32 v205, v136, v140
	v_cvt_pk_bf16_f32 v206, v144, v148
	v_cvt_pk_bf16_f32 v207, v152, v156
	global_store_dwordx4 v183, v[204:207], s[84:85]
	v_cvt_pk_bf16_f32 v208, v129, v133
	v_cvt_pk_bf16_f32 v209, v137, v141
	v_cvt_pk_bf16_f32 v210, v145, v149
	v_cvt_pk_bf16_f32 v211, v153, v157
	global_store_dwordx4 v184, v[208:211], s[84:85]
	v_cvt_pk_bf16_f32 v212, v130, v134
	v_cvt_pk_bf16_f32 v213, v138, v142
	v_cvt_pk_bf16_f32 v214, v146, v150
	v_cvt_pk_bf16_f32 v215, v154, v158
	global_store_dwordx4 v185, v[212:215], s[84:85]
	v_cvt_pk_bf16_f32 v216, v131, v135
	v_cvt_pk_bf16_f32 v217, v139, v143
	v_cvt_pk_bf16_f32 v218, v147, v151
	v_cvt_pk_bf16_f32 v219, v155, v159
	global_store_dwordx4 v186, v[216:219], s[84:85]
	s_add_u32 s81, s81, 0x300
	s_cmp_lt_u32 s81, 0x2000
	s_cbranch_scc0 .Ltr_done_t1vt
.Ltr_st2_t1vt:
	s_cmp_lt_u32 s79, 0x2000
	s_cbranch_scc0 .Ltr_nl2_t1vt
	s_lshr_b32 s89, s79, 9
	s_and_b32 s88, s79, 0x1ff
	s_lshr_b32 s86, s88, 5
	s_and_b32 s87, s88, 0x1f
	s_mul_i32 s88, s86, 0x40000
	s_lshl_b32 s87, s87, 7
	s_add_u32 s88, s88, s87
	s_mul_i32 s87, s89, 0x400000
	s_add_u32 s88, s88, s87
	s_add_u32 s82, s18, s88
	s_addc_u32 s83, s19, 0
	global_load_dwordx4 v[40:43], v36, s[82:83]
	global_load_dwordx4 v[44:47], v37, s[82:83]
	global_load_dwordx4 v[48:51], v72, s[82:83]
	global_load_dwordx4 v[52:55], v73, s[82:83]
	global_load_dwordx4 v[56:59], v74, s[82:83]
	global_load_dwordx4 v[60:63], v75, s[82:83]
	global_load_dwordx4 v[64:67], v76, s[82:83]
	global_load_dwordx4 v[68:71], v182, s[82:83]
	s_waitcnt vmcnt(16)
	s_branch .Ltr_pr2_t1vt

; #define LAS __attribute__((address_space(3)))
; __device__ __forceinline__ unsigned cvtpk(float lo, float hi) { f32x2_t v = {lo, hi}; bf16x2_t b = __builtin_convertvector(v, bf16x2_t); return __builtin_bit_cast(unsigned, b); }
; template <int MODE>
; __device__ __forceinline__ void transpose_item(const float* W, int N, bf16_t* WT, int ldt, int coff, LAS float* scr, int item, int lane, const float* g) {
;     const int nblk = N / 32, kb = item / nblk, nb = item % nblk, k0 = 64 * kb, n0 = 32 * nb;
; #pragma unroll 8
;     for (int i = 0; i < 32; ++i) { const int kk = 2 * i + (lane >> 5); float v = W[(size_t)(k0 + kk) * N + n0 + (lane & 31)]; if (MODE >= 1) v *= g[k0 + kk]; scr[kk * 33 + (lane & 31)] = v; }
;     asm volatile("s_waitcnt lgkmcnt(0)" ::: "memory");
;     const int c = lane & 7;
; #pragma unroll
;     for (int j = 0; j < 4; ++j) {
;         const int n = (lane >> 3) + 8 * j; const LAS float* s = scr + (8 * c) * 33 + n;
;         u32x4 o; o.x = cvtpk(s[0 * 33], s[1 * 33]); o.y = cvtpk(s[2 * 33], s[3 * 33]); o.z = cvtpk(s[4 * 33], s[5 * 33]); o.w = cvtpk(s[6 * 33], s[7 * 33]);
;         int dr = n0 + n;
;         if (MODE == 1) { dr = (dr < DFF) ? 256 * (dr >> 7) + (dr & 127) : 256 * ((dr - DFF) >> 7) + 128 + ((dr - DFF) & 127); }
;         if (MODE == 2) {
;             if (dr >= 6144) { const int t = dr - 6144, ch = t & 2047; dr = 6144 + 256 * (ch >> 7) + ((t >> 11) << 7) + (ch & 127); }
;             else if (dr >= 4096) { const int t = dr - 4096, ch = t & 1023; dr = 4096 + 256 * (ch >> 7) + ((t >> 10) << 7) + (ch & 127); }
;         }
;         *(u32x4*)(WT + (size_t)dr * ldt + coff + k0 + 8 * c) = o;
;     }
;     asm volatile("s_waitcnt lgkmcnt(0)" ::: "memory");
; }
; __global__ void __launch_bounds__(512, 2) mk_fwd(Args a) {
;     ...
;         for (size_t i = (size_t)gw; i < (size_t)DBATCH * PAST * 1024 / 512; i += NGW) {
;             const float* s = a.in[I_CK] + i * 512 + lane * 8; const f32x4 v0 = *(const f32x4*)s, v1 = *(const f32x4*)(s + 4);
.Ltr_pr2_t1vt:
	s_add_u32 s79, s79, 0x300
	s_lshr_b32 s89, s81, 9
	s_and_b32 s88, s81, 0x1ff
	s_lshr_b32 s86, s88, 5
	s_and_b32 s87, s88, 0x1f
	s_mul_i32 s88, s87, 0x10000
	s_lshl_b32 s86, s86, 7
	s_add_u32 s88, s88, s86
	s_mul_i32 s87, s89, 0x200000
	s_add_u32 s88, s88, s87
	s_add_u32 s84, s74, s88
	s_addc_u32 s85, s75, 0
	ds_write_b32 v188, v96 offset:0
	ds_write_b32 v188, v97 offset:4
	ds_write_b32 v188, v98 offset:8
	ds_write_b32 v188, v99 offset:12
	ds_write_b32 v188, v100 offset:1056
	ds_write_b32 v188, v101 offset:1060
	ds_write_b32 v188, v102 offset:1064
	ds_write_b32 v188, v103 offset:1068
	ds_write_b32 v188, v104 offset:2112
	ds_write_b32 v188, v105 offset:2116
	ds_write_b32 v188, v106 offset:2120
	ds_write_b32 v188, v107 offset:2124
	ds_write_b32 v188, v108 offset:3168
	ds_write_b32 v188, v109 offset:3172
	ds_write_b32 v188, v110 offset:3176
	ds_write_b32 v188, v111 offset:3180
	ds_write_b32 v188, v112 offset:4224
	ds_write_b32 v188, v113 offset:4228
	ds_write_b32 v188, v114 offset:4232
	ds_write_b32 v188, v115 offset:4236
	ds_write_b32 v188, v116 offset:5280
	ds_write_b32 v188, v117 offset:5284
	ds_write_b32 v188, v118 offset:5288
	ds_write_b32 v188, v119 offset:5292
	ds_write_b32 v188, v120 offset:6336
	ds_write_b32 v188, v121 offset:6340
	ds_write_b32 v188, v122 offset:6344
	ds_write_b32 v188, v123 offset:6348
	ds_write_b32 v188, v124 offset:7392
	ds_write_b32 v188, v125 offset:7396
	ds_write_b32 v188, v126 offset:7400
	ds_write_b32 v188, v127 offset:7404
	s_waitcnt lgkmcnt(0)
	ds_read2_b32 v[128:129], v189 offset0:0 offset1:8
	ds_read2_b32 v[132:133], v189 offset0:33 offset1:41
	ds_read2_b32 v[136:137], v189 offset0:66 offset1:74
	ds_read2_b32 v[140:141], v189 offset0:99 offset1:107
	ds_read2_b32 v[144:145], v189 offset0:132 offset1:140
	ds_read2_b32 v[148:149], v189 offset0:165 offset1:173
	ds_read2_b32 v[152:153], v189 offset0:198 offset1:206
	ds_read2_b32 v[156:157], v189 offset0:231 offset1:239
	ds_read2_b32 v[130:131], v189 offset0:16 offset1:24
	ds_read2_b32 v[134:135], v189 offset0:49 offset1:57
	ds_read2_b32 v[138:139], v189 offset0:82 offset1:90
	ds_read2_b32 v[142:143], v189 offset0:115 offset1:123
	ds_read2_b32 v[146:147], v189 offset0:148 offset1:156
	ds_read2_b32 v[150:151], v189 offset0:181 offset1:189
	ds_read2_b32 v[154:155], v189 offset0:214 offset1:222
	ds_read2_b32 v[158:159], v189 offset0:247 offset1:255
	s_waitcnt lgkmcnt(0)
	v_cvt_pk_bf16_f32 v204, v128, v132
	v_cvt_pk_bf16_f32 v205, v136, v140
	v_cvt_pk_bf16_f32 v206, v144, v148
	v_cvt_pk_bf16_f32 v207, v152, v156
	global_store_dwordx4 v183, v[204:207], s[84:85]
	v_cvt_pk_bf16_f32 v208, v129, v133
	v_cvt_pk_bf16_f32 v209, v137, v141
	v_cvt_pk_bf16_f32 v210, v145, v149
	v_cvt_pk_bf16_f32 v211, v153, v157
	global_store_dwordx4 v184, v[208:211], s[84:85]
	v_cvt_pk_bf16_f32 v212, v130, v134
	v_cvt_pk_bf16_f32 v213, v138, v142
	v_cvt_pk_bf16_f32 v214, v146, v150
	v_cvt_pk_bf16_f32 v215, v154, v158
	global_store_dwordx4 v185, v[212:215], s[84:85]
	v_cvt_pk_bf16_f32 v216, v131, v135
	v_cvt_pk_bf16_f32 v217, v139, v143
	v_cvt_pk_bf16_f32 v218, v147, v151
	v_cvt_pk_bf16_f32 v219, v155, v159
	global_store_dwordx4 v186, v[216:219], s[84:85]
	s_add_u32 s81, s81, 0x300
	s_cmp_lt_u32 s81, 0x2000
	s_cbranch_scc0 .Ltr_done_t1vt
	s_branch .Ltr_st0_t1vt
.Ltr_done_t1vt:
	v_lshlrev_b32_e32 v0, 5, v220
	v_lshlrev_b32_e32 v1, 4, v220
	s_mov_b32 s79, s67
; __device__ __forceinline__ unsigned xb_add(unsigned* p, unsigned v) { return __hip_atomic_fetch_add(p, v, __ATOMIC_RELAXED, __HIP_MEMORY_SCOPE_AGENT); }
; __device__ __forceinline__ void xcd_barrier(const XcdBarrier& b) {
;     asm volatile("s_waitcnt vmcnt(0)" ::: "memory");
;     __syncthreads();
;     if (threadIdx.x == 0) {
;         unsigned* bar = b.bar;
;         __builtin_amdgcn_s_waitcnt(0);
;         unsigned nloc = b.st[0], nx = b.st[1];
;         if (nloc == 0u) { xcd_barrier_complete(bar, b.x, nloc, nx); b.st[0] = nloc; b.st[1] = nx; }
;         const unsigned old = xb_add(&bar[XB_XSUB(b.x)], 1u);
; __global__ void __launch_bounds__(512, 2) mk_fwd(Args a) {
;     ...
;         for (size_t i = (size_t)gw; i < (size_t)DBATCH * PAST * 1024 / 512; i += NGW) {
;             const float* s = a.in[I_CK] + i * 512 + lane * 8; const f32x4 v0 = *(const f32x4*)s, v1 = *(const f32x4*)(s + 4);
;             store_bf8(KC + i * 512 + lane * 8, v0, v1);
;         }
.Lkc_loop:
	s_cmp_lt_u32 s79, 0x8000
	s_cbranch_scc0 .Ltail_done
	s_add_u32 s81, s79, 0x0
	s_cmp_lt_u32 s81, 0x8000
	s_cselect_b32 s81, s81, s79
	s_lshl_b32 s86, s81, 11
	s_add_u32 s82, s34, s86
	s_addc_u32 s83, s35, 0
	global_load_dwordx4 v[4:7], v0, s[82:83]
	global_load_dwordx4 v[8:11], v0, s[82:83] offset:16
	s_add_u32 s81, s79, 0x300
	s_cmp_lt_u32 s81, 0x8000
	s_cselect_b32 s81, s81, s79
	s_lshl_b32 s86, s81, 11
	s_add_u32 s82, s34, s86
	s_addc_u32 s83, s35, 0
	global_load_dwordx4 v[12:15], v0, s[82:83]
	global_load_dwordx4 v[16:19], v0, s[82:83] offset:16
	s_add_u32 s81, s79, 0x600
	s_cmp_lt_u32 s81, 0x8000
	s_cselect_b32 s81, s81, s79
	s_lshl_b32 s86, s81, 11
	s_add_u32 s82, s34, s86
	s_addc_u32 s83, s35, 0
	global_load_dwordx4 v[20:23], v0, s[82:83]
	global_load_dwordx4 v[24:27], v0, s[82:83] offset:16
	s_add_u32 s81, s79, 0x900
	s_cmp_lt_u32 s81, 0x8000
	s_cselect_b32 s81, s81, s79
	s_lshl_b32 s86, s81, 11
	s_add_u32 s82, s34, s86
	s_addc_u32 s83, s35, 0
	global_load_dwordx4 v[28:31], v0, s[82:83]
	global_load_dwordx4 v[32:35], v0, s[82:83] offset:16
	s_add_u32 s81, s79, 0xc00
	s_cmp_lt_u32 s81, 0x8000
	s_cselect_b32 s81, s81, s79
	s_lshl_b32 s86, s81, 11
	s_add_u32 s82, s34, s86
	s_addc_u32 s83, s35, 0
	global_load_dwordx4 v[40:43], v0, s[82:83]
	global_load_dwordx4 v[44:47], v0, s[82:83] offset:16
	s_add_u32 s81, s79, 0xf00
	s_cmp_lt_u32 s81, 0x8000
	s_cselect_b32 s81, s81, s79
	s_lshl_b32 s86, s81, 11
	s_add_u32 s82, s34, s86
	s_addc_u32 s83, s35, 0
	global_load_dwordx4 v[48:51], v0, s[82:83]
	global_load_dwordx4 v[52:55], v0, s[82:83] offset:16
	s_add_u32 s81, s79, 0x1200
	s_cmp_lt_u32 s81, 0x8000
	s_cselect_b32 s81, s81, s79
	s_lshl_b32 s86, s81, 11
	s_add_u32 s82, s34, s86
	s_addc_u32 s83, s35, 0
	global_load_dwordx4 v[56:59], v0, s[82:83]
	global_load_dwordx4 v[60:63], v0, s[82:83] offset:16
	s_add_u32 s81, s79, 0x1500
	s_cmp_lt_u32 s81, 0x8000
	s_cselect_b32 s81, s81, s79
	s_lshl_b32 s86, s81, 11
	s_add_u32 s82, s34, s86
	s_addc_u32 s83, s35, 0
	global_load_dwordx4 v[64:67], v0, s[82:83]
	global_load_dwordx4 v[68:71], v0, s[82:83] offset:16
	s_waitcnt vmcnt(14)
	v_cvt_pk_bf16_f32 v72, v4, v5
	v_cvt_pk_bf16_f32 v73, v6, v7
	v_cvt_pk_bf16_f32 v74, v8, v9
	v_cvt_pk_bf16_f32 v75, v10, v11
	s_add_u32 s81, s79, 0x0
	s_cmp_lt_u32 s81, 0x8000
	s_cselect_b32 s81, s81, s79
	s_lshl_b32 s86, s81, 10
	s_add_u32 s84, s76, s86
	s_addc_u32 s85, s77, 0
	global_store_dwordx4 v1, v[72:75], s[84:85]
	s_waitcnt vmcnt(13)
	v_cvt_pk_bf16_f32 v96, v12, v13
	v_cvt_pk_bf16_f32 v97, v14, v15
	v_cvt_pk_bf16_f32 v98, v16, v17
	v_cvt_pk_bf16_f32 v99, v18, v19
	s_add_u32 s81, s79, 0x300
	s_cmp_lt_u32 s81, 0x8000
	s_cselect_b32 s81, s81, s79
	s_lshl_b32 s86, s81, 10
	s_add_u32 s84, s76, s86
	s_addc_u32 s85, s77, 0
	global_store_dwordx4 v1, v[96:99], s[84:85]
	s_waitcnt vmcnt(12)
	v_cvt_pk_bf16_f32 v100, v20, v21
	v_cvt_pk_bf16_f32 v101, v22, v23
	v_cvt_pk_bf16_f32 v102, v24, v25
	v_cvt_pk_bf16_f32 v103, v26, v27
	s_add_u32 s81, s79, 0x600
	s_cmp_lt_u32 s81, 0x8000
	s_cselect_b32 s81, s81, s79
	s_lshl_b32 s86, s81, 10
	s_add_u32 s84, s76, s86
	s_addc_u32 s85, s77, 0
	global_store_dwordx4 v1, v[100:103], s[84:85]
	s_waitcnt vmcnt(11)
	v_cvt_pk_bf16_f32 v104, v28, v29
	v_cvt_pk_bf16_f32 v105, v30, v31
	v_cvt_pk_bf16_f32 v106, v32, v33
	v_cvt_pk_bf16_f32 v107, v34, v35
	s_add_u32 s81, s79, 0x900
	s_cmp_lt_u32 s81, 0x8000
	s_cselect_b32 s81, s81, s79
	s_lshl_b32 s86, s81, 10
	s_add_u32 s84, s76, s86
	s_addc_u32 s85, s77, 0
	global_store_dwordx4 v1, v[104:107], s[84:85]
	s_waitcnt vmcnt(10)
	v_cvt_pk_bf16_f32 v108, v40, v41
	v_cvt_pk_bf16_f32 v109, v42, v43
	v_cvt_pk_bf16_f32 v110, v44, v45
	v_cvt_pk_bf16_f32 v111, v46, v47
	s_add_u32 s81, s79, 0xc00
	s_cmp_lt_u32 s81, 0x8000
	s_cselect_b32 s81, s81, s79
	s_lshl_b32 s86, s81, 10
	s_add_u32 s84, s76, s86
	s_addc_u32 s85, s77, 0
	global_store_dwordx4 v1, v[108:111], s[84:85]
	s_waitcnt vmcnt(9)
	v_cvt_pk_bf16_f32 v112, v48, v49
	v_cvt_pk_bf16_f32 v113, v50, v51
	v_cvt_pk_bf16_f32 v114, v52, v53
	v_cvt_pk_bf16_f32 v115, v54, v55
	s_add_u32 s81, s79, 0xf00
	s_cmp_lt_u32 s81, 0x8000
	s_cselect_b32 s81, s81, s79
	s_lshl_b32 s86, s81, 10
	s_add_u32 s84, s76, s86
	s_addc_u32 s85, s77, 0
	global_store_dwordx4 v1, v[112:115], s[84:85]
	s_waitcnt vmcnt(8)
	v_cvt_pk_bf16_f32 v116, v56, v57
	v_cvt_pk_bf16_f32 v117, v58, v59
	v_cvt_pk_bf16_f32 v118, v60, v61
	v_cvt_pk_bf16_f32 v119, v62, v63
	s_add_u32 s81, s79, 0x1200
	s_cmp_lt_u32 s81, 0x8000
	s_cselect_b32 s81, s81, s79
	s_lshl_b32 s86, s81, 10
	s_add_u32 s84, s76, s86
	s_addc_u32 s85, s77, 0
	global_store_dwordx4 v1, v[116:119], s[84:85]
	s_waitcnt vmcnt(7)
	v_cvt_pk_bf16_f32 v120, v64, v65
	v_cvt_pk_bf16_f32 v121, v66, v67
	v_cvt_pk_bf16_f32 v122, v68, v69
	v_cvt_pk_bf16_f32 v123, v70, v71
	s_add_u32 s81, s79, 0x1500
	s_cmp_lt_u32 s81, 0x8000
	s_cselect_b32 s81, s81, s79
	s_lshl_b32 s86, s81, 10
	s_add_u32 s84, s76, s86
	s_addc_u32 s85, s77, 0
	global_store_dwordx4 v1, v[120:123], s[84:85]
	s_add_u32 s79, s79, 0x1800
	s_branch .Lkc_loop
.Ltail_done:
.LBB0_416:
	s_cmp_gt_i32 s71, 2
	s_cselect_b64 s[0:1], -1, 0
	s_and_b64 s[4:5], s[10:11], s[0:1]
	s_andn2_b64 vcc, exec, s[4:5]
	s_cbranch_vccnz .LBB0_471
	s_waitcnt vmcnt(0)
	s_barrier
	s_and_saveexec_b64 s[4:5], s[12:13]
	s_cbranch_execz .LBB0_470
	s_add_i32 s6, 0, 0x26020
	v_mov_b32_e32 v0, s6
	s_waitcnt vmcnt(0) expcnt(0) lgkmcnt(0)
	ds_read_b32 v2, v0
	s_add_i32 s6, 0, 0x26024
	v_mov_b32_e32 v0, s6
	ds_read_b32 v0, v0
	s_waitcnt lgkmcnt(1)
	v_cmp_ne_u32_e32 vcc, 0, v2
	s_cbranch_vccnz .LBB0_434
	v_readlane_b32 s6, v250, 0
	v_readlane_b32 s7, v250, 1
	s_load_dwordx2 s[10:11], s[6:7], 0x4
	s_add_u32 s6, s68, 0x4200
	s_addc_u32 s7, s69, 0
	s_add_u32 s8, s68, 0x4400
	s_addc_u32 s9, s69, 0
	s_waitcnt lgkmcnt(0)
	s_mul_i32 s34, s10, s3
	s_add_u32 s10, s68, 0x4500
	s_mul_i32 s34, s34, s11
	s_addc_u32 s11, s69, 0
	s_add_u32 s18, s68, 0x4600
	s_addc_u32 s19, s69, 0
	s_add_u32 s36, s68, 0x4700
	s_addc_u32 s37, s69, 0
	s_add_u32 s40, s68, 0x4800
	s_addc_u32 s41, s69, 0
	s_add_u32 s42, s68, 0x4900
	s_addc_u32 s43, s69, 0
	s_add_u32 s50, s68, 0x4a00
	s_addc_u32 s51, s69, 0
	s_add_u32 s52, s68, 0x4b00
	s_addc_u32 s53, s69, 0
	s_add_u32 s66, s68, 0x4c00
	s_addc_u32 s67, s69, 0
	s_add_u32 s74, s68, 0x4d00
	s_addc_u32 s75, s69, 0
	s_add_u32 s76, s68, 0x4e00
	s_addc_u32 s77, s69, 0
	s_add_u32 s78, s68, 0x4f00
	s_addc_u32 s79, s69, 0
	s_add_u32 s82, s68, 0x5000
	s_addc_u32 s83, s69, 0
	s_add_u32 s84, s68, 0x5100
	s_addc_u32 s85, s69, 0
	s_add_u32 s86, s68, 0x5200
	s_addc_u32 s87, s69, 0
	s_add_u32 s88, s68, 0x5300
	s_addc_u32 s89, s69, 0
	s_mov_b32 s35, 1
	v_mov_b32_e32 v16, 0
	s_branch .LBB0_422
